# merge phase: 8 context tiles x 3 branch steps spread over 24 workgroups with flag hand-off (was 8 WGs x 6 units)
# baseline (speedup 1.0000x reference)
;     __host__ __device__ bool next(int i, Unit& u) const {
;         const long L = (long)i * G + c; if (L >= nwg) return false;
;         int wgid = (int)L; { const int q = nwg / NXCD, r = nwg % NXCD, xcd = wgid % NXCD, off = wgid / NXCD; wgid = (xcd < r ? xcd * (q + 1) : r * (q + 1) + (xcd - r) * q) + off; }
;         const int nig = WGM * nN, gid = wgid / nig, fm = gid * WGM, gsz = (nM - fm) < WGM ? (nM - fm) : WGM;
;         u.pm = fm + ((wgid % nig) % gsz); u.pn = (wgid % nig) / gsz; u.koff = 0; u.nt = 0; return true;
.LBB0_508:
	s_add_i32 s47, s47, 1
	s_mul_i32 s4, s34, 0xaaab
	s_lshr_b32 s4, s4, 17
	s_mul_i32 s5, s4, 3
	s_sub_i32 s5, s34, s5
	s_cmp_eq_u32 s5, 0
	s_cselect_b32 s5, 0, 0x10000000
	s_cmp_lt_u32 s34, 24
	s_cselect_b32 s5, s5, 0x10000000
	s_lshl_b32 s18, s47, 8
	s_add_i32 s18, s18, s4
	s_add_i32 s18, s18, s5
	s_mov_b32 s19, 0
	v_mov_b64_e32 v[2:3], s[94:95]
	v_cmp_ge_i64_e32 vcc, s[18:19], v[2:3]
	v_cmp_lt_i64_e64 s[4:5], s[18:19], v[2:3]
	s_cbranch_vccnz .LBB0_510
	s_ashr_i32 s14, s18, 31
	s_lshr_b32 s14, s14, 29
	s_add_i32 s14, s18, s14
	s_ashr_i32 s15, s14, 3
	s_and_b32 s14, s14, -8
	s_sub_i32 s14, s18, s14
	s_cmp_lt_i32 s14, 0
	s_cselect_b32 s16, s41, s39
	s_mul_i32 s14, s16, s14
	s_add_i32 s14, s14, s15
	s_ashr_i32 s15, s14, 31
	s_lshr_b32 s15, s15, 27
	s_add_i32 s15, s14, s15
	s_ashr_i32 s16, s15, 5
	s_lshl_b32 s16, s16, 3
	s_sub_i32 s17, s50, s16
	s_min_i32 s17, s17, 8
	s_abs_i32 s18, s17
	v_cvt_f32_u32_e32 v2, s18
	s_sub_i32 s20, 0, s18
	s_andn2_b32 s15, s15, 31
	s_sub_i32 s15, s14, s15
	v_rcp_iflag_f32_e32 v2, v2
	s_abs_i32 s14, s15
	s_xor_b32 s19, s15, s17
	s_ashr_i32 s19, s19, 31
	v_mul_f32_e32 v2, 0x4f7ffffe, v2
	v_cvt_u32_f32_e32 v2, v2
	s_nop 0
	v_readfirstlane_b32 s21, v2
	s_mul_i32 s20, s20, s21
	s_mul_hi_u32 s20, s21, s20
	s_add_i32 s21, s21, s20
	s_mul_hi_u32 s20, s14, s21
	s_mul_i32 s21, s20, s18
	s_sub_i32 s14, s14, s21
	s_add_i32 s23, s20, 1
	s_sub_i32 s21, s14, s18
	s_cmp_ge_u32 s14, s18
	s_cselect_b32 s20, s23, s20
	s_cselect_b32 s14, s21, s14
	s_add_i32 s21, s20, 1
	s_cmp_ge_u32 s14, s18
	s_cselect_b32 s14, s21, s20
	s_xor_b32 s14, s14, s19
	s_sub_i32 s14, s14, s19
	s_mul_i32 s17, s14, s17
	s_sub_i32 s15, s15, s17
	s_add_i32 s16, s15, s16

; __device__ __forceinline__ unsigned cvtpk(float lo, float hi) { const f32x2_t v = {lo, hi}; const bf16x2_t b = __builtin_convertvector(v, bf16x2_t); return __builtin_bit_cast(unsigned, b); }
; __device__ __forceinline__ float bf_lo(unsigned u) { return __uint_as_float(u << 16); }
; __device__ __forceinline__ float bf_hi(unsigned u) { return __uint_as_float(u & 0xffff0000u); }
;     __device__ __forceinline__ void operator()(const f32x4 (&acc)[2][2][4][2], const pg8::Unit& u, int wr, int wc, int fr, int fq) const {
;         const int row0 = u.pm * 256 + wr * 64 + fr, col0 = u.pn * 256 + wc * 32 + 8 * fq;
; #pragma unroll
;         for (int ai = 0; ai < 2; ++ai)
; #pragma unroll
;             for (int m = 0; m < 4; ++m) {
;                 const size_t r = (size_t)(row0 + ai * 128 + m * 16);
; #pragma unroll
;                 for (int bj = 0; bj < 2; ++bj) {
;                     const int c = col0 + 128 * bj;
;                     const u32x2 g = *(const u32x2*)((const unsigned char*)G + r * 3072 + STEP * 1024 + c);
;                     f32x4 v0 = acc[ai][bj][m][0], v1 = acc[ai][bj][m][1];
;                     constexpr float S8 = 1.f / 255.f;
;                     v0 = v0 * ((f32x4){(float)(g.x & 255u), (float)((g.x >> 8) & 255u), (float)((g.x >> 16) & 255u), (float)(g.x >> 24)} * S8);
;                     v1 = v1 * ((f32x4){(float)(g.y & 255u), (float)((g.y >> 8) & 255u), (float)((g.y >> 16) & 255u), (float)(g.y >> 24)} * S8);
;                     bf16_t* tp = (STEP < 2 ? T : Z) + r * 1024 + c;
;                     if (STEP > 0) { const u32x4 t = *(const u32x4*)(T + r * 1024 + c);
;                         v0 = v0 + (f32x4){bf_lo(t.x), bf_hi(t.x), bf_lo(t.y), bf_hi(t.y)}; v1 = v1 + (f32x4){bf_lo(t.z), bf_hi(t.z), bf_lo(t.w), bf_hi(t.w)}; }
;                     u32x4 w; w.x = cvtpk(v0[0], v0[1]); w.y = cvtpk(v0[2], v0[3]); w.z = cvtpk(v1[0], v1[1]); w.w = cvtpk(v1[2], v1[3]); *(u32x4*)tp = w;
;                 }
.LBB0_514:
	v_lshl_add_u32 v142, s24, 8, v146
	v_lshl_or_b32 v140, s22, 8, v148
	v_mov_b64_e32 v[144:145], s[8:9]
	v_mad_i64_i32 v[152:153], s[22:23], v142, s86, v[144:145]
	v_ashrrev_i32_e32 v141, 31, v140
	v_lshl_add_u64 v[152:153], v[152:153], 0, v[140:141]
	global_load_dwordx2 v[154:155], v[152:153], off
	v_ashrrev_i32_e32 v143, 31, v142
	v_lshlrev_b64 v[150:151], 11, v[142:143]
	s_andn2_b64 vcc, exec, s[4:5]
	s_waitcnt vmcnt(0)
	v_cvt_f32_ubyte3_e32 v157, v154
	v_cvt_f32_ubyte2_e32 v156, v154
	v_cvt_f32_ubyte1_e32 v159, v154
	v_cvt_f32_ubyte0_e32 v158, v154
	v_pk_mul_f32 v[158:159], v[158:159], s[72:73] op_sel_hi:[1,0]
	v_pk_mul_f32 v[156:157], v[156:157], s[72:73] op_sel_hi:[1,0]
	v_pk_mul_f32 v[126:127], v[126:127], v[158:159]
	v_pk_mul_f32 v[128:129], v[128:129], v[156:157]
	v_cvt_f32_ubyte3_e32 v157, v155
	v_cvt_f32_ubyte2_e32 v156, v155
	v_cvt_f32_ubyte1_e32 v159, v155
	v_cvt_f32_ubyte0_e32 v158, v155
	v_pk_mul_f32 v[154:155], v[158:159], s[72:73] op_sel_hi:[1,0]
	v_pk_mul_f32 v[156:157], v[156:157], s[72:73] op_sel_hi:[1,0]
	v_pk_mul_f32 v[154:155], v[122:123], v[154:155]
	v_pk_mul_f32 v[156:157], v[124:125], v[156:157]
	v_lshl_add_u64 v[124:125], s[10:11], 0, v[150:151]
	v_lshlrev_b64 v[122:123], 1, v[140:141]
	v_lshl_add_u64 v[150:151], v[124:125], 0, v[122:123]
	v_cvt_pk_bf16_f32 v124, v126, v127
	v_cvt_pk_bf16_f32 v125, v128, v129
	v_cvt_pk_bf16_f32 v126, v154, v155
	v_cvt_pk_bf16_f32 v127, v156, v157
	global_store_dwordx4 v[150:151], v[124:127], off
	global_load_dwordx2 v[124:125], v[152:153], off offset:128
	s_waitcnt vmcnt(0)
	v_cvt_f32_ubyte1_e32 v129, v124
	v_cvt_f32_ubyte3_e32 v127, v124
	v_cvt_f32_ubyte2_e32 v126, v124
	v_cvt_f32_ubyte0_e32 v128, v124
	v_pk_mul_f32 v[128:129], v[128:129], s[72:73] op_sel_hi:[1,0]
	v_pk_mul_f32 v[126:127], v[126:127], s[72:73] op_sel_hi:[1,0]
	v_pk_mul_f32 v[118:119], v[118:119], v[128:129]
	v_pk_mul_f32 v[120:121], v[120:121], v[126:127]
	v_cvt_f32_ubyte3_e32 v127, v125
	v_cvt_f32_ubyte2_e32 v126, v125
	v_cvt_f32_ubyte1_e32 v129, v125
	v_cvt_f32_ubyte0_e32 v128, v125
	v_pk_mul_f32 v[124:125], v[128:129], s[72:73] op_sel_hi:[1,0]
	v_pk_mul_f32 v[126:127], v[126:127], s[72:73] op_sel_hi:[1,0]
	s_nop 0
	v_pk_mul_f32 v[126:127], v[116:117], v[126:127]
	v_pk_mul_f32 v[116:117], v[114:115], v[124:125]
	v_cvt_pk_bf16_f32 v114, v118, v119
	v_cvt_pk_bf16_f32 v115, v120, v121
	v_cvt_pk_bf16_f32 v116, v116, v117
	v_cvt_pk_bf16_f32 v117, v126, v127
	global_store_dwordx4 v[150:151], v[114:117], off offset:256
	s_nop 1
	v_or_b32_e32 v114, 16, v142
	v_ashrrev_i32_e32 v115, 31, v114
	v_lshlrev_b64 v[116:117], 11, v[114:115]
	v_mad_i64_i32 v[114:115], s[22:23], v114, s86, v[144:145]
	v_lshl_add_u64 v[114:115], v[114:115], 0, v[140:141]
	global_load_dwordx2 v[118:119], v[114:115], off
	s_waitcnt vmcnt(0)
	v_cvt_f32_ubyte3_e32 v121, v118
	v_cvt_f32_ubyte2_e32 v120, v118
	v_cvt_f32_ubyte1_e32 v125, v118
	v_cvt_f32_ubyte0_e32 v124, v118
	v_pk_mul_f32 v[124:125], v[124:125], s[72:73] op_sel_hi:[1,0]
	v_pk_mul_f32 v[120:121], v[120:121], s[72:73] op_sel_hi:[1,0]
	v_pk_mul_f32 v[110:111], v[110:111], v[124:125]
	v_pk_mul_f32 v[112:113], v[112:113], v[120:121]
	v_cvt_f32_ubyte3_e32 v121, v119
	v_cvt_f32_ubyte2_e32 v120, v119
	v_cvt_f32_ubyte1_e32 v125, v119
	v_cvt_f32_ubyte0_e32 v124, v119
	v_pk_mul_f32 v[118:119], v[124:125], s[72:73] op_sel_hi:[1,0]
	v_pk_mul_f32 v[120:121], v[120:121], s[72:73] op_sel_hi:[1,0]
	s_nop 0
	v_pk_mul_f32 v[120:121], v[108:109], v[120:121]
	v_pk_mul_f32 v[108:109], v[106:107], v[118:119]
	v_lshl_add_u64 v[106:107], s[10:11], 0, v[116:117]
	v_lshl_add_u64 v[116:117], v[106:107], 0, v[122:123]
	v_cvt_pk_bf16_f32 v106, v110, v111
	v_cvt_pk_bf16_f32 v107, v112, v113
	v_cvt_pk_bf16_f32 v108, v108, v109
	v_cvt_pk_bf16_f32 v109, v120, v121
	global_store_dwordx4 v[116:117], v[106:109], off
	global_load_dwordx2 v[106:107], v[114:115], off offset:128
	s_waitcnt vmcnt(0)
	v_cvt_f32_ubyte1_e32 v111, v106
	v_cvt_f32_ubyte3_e32 v109, v106
	v_cvt_f32_ubyte2_e32 v108, v106
	v_cvt_f32_ubyte0_e32 v110, v106
	v_pk_mul_f32 v[110:111], v[110:111], s[72:73] op_sel_hi:[1,0]
	v_pk_mul_f32 v[108:109], v[108:109], s[72:73] op_sel_hi:[1,0]
	v_pk_mul_f32 v[102:103], v[102:103], v[110:111]
	v_pk_mul_f32 v[104:105], v[104:105], v[108:109]
	v_cvt_f32_ubyte3_e32 v109, v107
	v_cvt_f32_ubyte2_e32 v108, v107
	v_cvt_f32_ubyte1_e32 v111, v107
	v_cvt_f32_ubyte0_e32 v110, v107
	v_pk_mul_f32 v[106:107], v[110:111], s[72:73] op_sel_hi:[1,0]
	v_pk_mul_f32 v[108:109], v[108:109], s[72:73] op_sel_hi:[1,0]
	s_nop 0
	v_pk_mul_f32 v[108:109], v[100:101], v[108:109]
	v_pk_mul_f32 v[100:101], v[98:99], v[106:107]
	v_cvt_pk_bf16_f32 v98, v102, v103
	v_cvt_pk_bf16_f32 v99, v104, v105
	v_cvt_pk_bf16_f32 v100, v100, v101
	v_cvt_pk_bf16_f32 v101, v108, v109
	global_store_dwordx4 v[116:117], v[98:101], off offset:256
	s_nop 1
	v_or_b32_e32 v98, 32, v142
	v_ashrrev_i32_e32 v99, 31, v98
	v_lshlrev_b64 v[100:101], 11, v[98:99]
	v_mad_i64_i32 v[98:99], s[22:23], v98, s86, v[144:145]
	v_lshl_add_u64 v[98:99], v[98:99], 0, v[140:141]
	global_load_dwordx2 v[102:103], v[98:99], off
	s_waitcnt vmcnt(0)
	v_cvt_f32_ubyte3_e32 v105, v102
	v_cvt_f32_ubyte2_e32 v104, v102
	v_cvt_f32_ubyte1_e32 v107, v102
	v_cvt_f32_ubyte0_e32 v106, v102
	v_pk_mul_f32 v[106:107], v[106:107], s[72:73] op_sel_hi:[1,0]
	v_pk_mul_f32 v[104:105], v[104:105], s[72:73] op_sel_hi:[1,0]
	v_pk_mul_f32 v[94:95], v[94:95], v[106:107]
	v_pk_mul_f32 v[96:97], v[96:97], v[104:105]
	v_cvt_f32_ubyte3_e32 v105, v103
	v_cvt_f32_ubyte2_e32 v104, v103
	v_cvt_f32_ubyte1_e32 v107, v103
	v_cvt_f32_ubyte0_e32 v106, v103
	v_pk_mul_f32 v[102:103], v[106:107], s[72:73] op_sel_hi:[1,0]
	v_pk_mul_f32 v[104:105], v[104:105], s[72:73] op_sel_hi:[1,0]
	s_nop 0
	v_pk_mul_f32 v[104:105], v[92:93], v[104:105]
	v_pk_mul_f32 v[92:93], v[90:91], v[102:103]
	v_lshl_add_u64 v[90:91], s[10:11], 0, v[100:101]
	v_lshl_add_u64 v[100:101], v[90:91], 0, v[122:123]
	v_cvt_pk_bf16_f32 v90, v94, v95
	v_cvt_pk_bf16_f32 v91, v96, v97
	v_cvt_pk_bf16_f32 v92, v92, v93
	v_cvt_pk_bf16_f32 v93, v104, v105
	global_store_dwordx4 v[100:101], v[90:93], off
	global_load_dwordx2 v[90:91], v[98:99], off offset:128
	s_waitcnt vmcnt(0)
; __device__ __forceinline__ unsigned cvtpk(float lo, float hi) { const f32x2_t v = {lo, hi}; const bf16x2_t b = __builtin_convertvector(v, bf16x2_t); return __builtin_bit_cast(unsigned, b); }
; __device__ __forceinline__ float bf_lo(unsigned u) { return __uint_as_float(u << 16); }
; __device__ __forceinline__ float bf_hi(unsigned u) { return __uint_as_float(u & 0xffff0000u); }
;     __device__ __forceinline__ void operator()(const f32x4 (&acc)[2][2][4][2], const pg8::Unit& u, int wr, int wc, int fr, int fq) const {
;         const int row0 = u.pm * 256 + wr * 64 + fr, col0 = u.pn * 256 + wc * 32 + 8 * fq;
; #pragma unroll
;         for (int ai = 0; ai < 2; ++ai)
; #pragma unroll
;             for (int m = 0; m < 4; ++m) {
;                 const size_t r = (size_t)(row0 + ai * 128 + m * 16);
; #pragma unroll
;                 for (int bj = 0; bj < 2; ++bj) {
;                     const int c = col0 + 128 * bj;
;                     const u32x2 g = *(const u32x2*)((const unsigned char*)G + r * 3072 + STEP * 1024 + c);
;                     f32x4 v0 = acc[ai][bj][m][0], v1 = acc[ai][bj][m][1];
;                     constexpr float S8 = 1.f / 255.f;
;                     v0 = v0 * ((f32x4){(float)(g.x & 255u), (float)((g.x >> 8) & 255u), (float)((g.x >> 16) & 255u), (float)(g.x >> 24)} * S8);
;                     v1 = v1 * ((f32x4){(float)(g.y & 255u), (float)((g.y >> 8) & 255u), (float)((g.y >> 16) & 255u), (float)(g.y >> 24)} * S8);
;                     bf16_t* tp = (STEP < 2 ? T : Z) + r * 1024 + c;
;                     if (STEP > 0) { const u32x4 t = *(const u32x4*)(T + r * 1024 + c);
;                         v0 = v0 + (f32x4){bf_lo(t.x), bf_hi(t.x), bf_lo(t.y), bf_hi(t.y)}; v1 = v1 + (f32x4){bf_lo(t.z), bf_hi(t.z), bf_lo(t.w), bf_hi(t.w)}; }
;                     u32x4 w; w.x = cvtpk(v0[0], v0[1]); w.y = cvtpk(v0[2], v0[3]); w.z = cvtpk(v1[0], v1[1]); w.w = cvtpk(v1[2], v1[3]); *(u32x4*)tp = w;
;                 }
	v_cvt_f32_ubyte1_e32 v95, v90
	v_cvt_f32_ubyte3_e32 v93, v90
	v_cvt_f32_ubyte2_e32 v92, v90
	v_cvt_f32_ubyte0_e32 v94, v90
	v_pk_mul_f32 v[94:95], v[94:95], s[72:73] op_sel_hi:[1,0]
	v_pk_mul_f32 v[92:93], v[92:93], s[72:73] op_sel_hi:[1,0]
	v_pk_mul_f32 v[86:87], v[86:87], v[94:95]
	v_pk_mul_f32 v[88:89], v[88:89], v[92:93]
	v_cvt_f32_ubyte3_e32 v93, v91
	v_cvt_f32_ubyte2_e32 v92, v91
	v_cvt_f32_ubyte1_e32 v95, v91
	v_cvt_f32_ubyte0_e32 v94, v91
	v_pk_mul_f32 v[90:91], v[94:95], s[72:73] op_sel_hi:[1,0]
	v_pk_mul_f32 v[92:93], v[92:93], s[72:73] op_sel_hi:[1,0]
	s_nop 0
	v_pk_mul_f32 v[92:93], v[84:85], v[92:93]
	v_pk_mul_f32 v[84:85], v[82:83], v[90:91]
	v_cvt_pk_bf16_f32 v82, v86, v87
	v_cvt_pk_bf16_f32 v83, v88, v89
	v_cvt_pk_bf16_f32 v84, v84, v85
	v_cvt_pk_bf16_f32 v85, v92, v93
	global_store_dwordx4 v[100:101], v[82:85], off offset:256
	s_nop 1
	v_or_b32_e32 v82, 48, v142
	v_ashrrev_i32_e32 v83, 31, v82
	v_lshlrev_b64 v[84:85], 11, v[82:83]
	v_mad_i64_i32 v[82:83], s[22:23], v82, s86, v[144:145]
	v_lshl_add_u64 v[82:83], v[82:83], 0, v[140:141]
	global_load_dwordx2 v[86:87], v[82:83], off
	s_waitcnt vmcnt(0)
	v_cvt_f32_ubyte3_e32 v89, v86
	v_cvt_f32_ubyte2_e32 v88, v86
	v_cvt_f32_ubyte1_e32 v91, v86
	v_cvt_f32_ubyte0_e32 v90, v86
	v_pk_mul_f32 v[90:91], v[90:91], s[72:73] op_sel_hi:[1,0]
	v_pk_mul_f32 v[88:89], v[88:89], s[72:73] op_sel_hi:[1,0]
	v_pk_mul_f32 v[78:79], v[78:79], v[90:91]
	v_pk_mul_f32 v[80:81], v[80:81], v[88:89]
	v_cvt_f32_ubyte3_e32 v89, v87
	v_cvt_f32_ubyte2_e32 v88, v87
	v_cvt_f32_ubyte1_e32 v91, v87
	v_cvt_f32_ubyte0_e32 v90, v87
	v_pk_mul_f32 v[86:87], v[90:91], s[72:73] op_sel_hi:[1,0]
	v_pk_mul_f32 v[88:89], v[88:89], s[72:73] op_sel_hi:[1,0]
	s_nop 0
	v_pk_mul_f32 v[88:89], v[76:77], v[88:89]
	v_pk_mul_f32 v[76:77], v[74:75], v[86:87]
	v_lshl_add_u64 v[74:75], s[10:11], 0, v[84:85]
	v_lshl_add_u64 v[84:85], v[74:75], 0, v[122:123]
	v_cvt_pk_bf16_f32 v74, v78, v79
	v_cvt_pk_bf16_f32 v75, v80, v81
	v_cvt_pk_bf16_f32 v76, v76, v77
	v_cvt_pk_bf16_f32 v77, v88, v89
	global_store_dwordx4 v[84:85], v[74:77], off
	global_load_dwordx2 v[74:75], v[82:83], off offset:128
	s_waitcnt vmcnt(0)
	v_cvt_f32_ubyte1_e32 v79, v74
	v_cvt_f32_ubyte3_e32 v77, v74
	v_cvt_f32_ubyte2_e32 v76, v74
	v_cvt_f32_ubyte0_e32 v78, v74
	v_pk_mul_f32 v[78:79], v[78:79], s[72:73] op_sel_hi:[1,0]
	v_pk_mul_f32 v[76:77], v[76:77], s[72:73] op_sel_hi:[1,0]
	v_pk_mul_f32 v[70:71], v[70:71], v[78:79]
	v_pk_mul_f32 v[72:73], v[72:73], v[76:77]
	v_cvt_f32_ubyte3_e32 v77, v75
	v_cvt_f32_ubyte2_e32 v76, v75
	v_cvt_f32_ubyte1_e32 v79, v75
	v_cvt_f32_ubyte0_e32 v78, v75
	v_pk_mul_f32 v[74:75], v[78:79], s[72:73] op_sel_hi:[1,0]
	v_pk_mul_f32 v[76:77], v[76:77], s[72:73] op_sel_hi:[1,0]
	s_nop 0
	v_pk_mul_f32 v[76:77], v[68:69], v[76:77]
	v_pk_mul_f32 v[68:69], v[66:67], v[74:75]
	v_cvt_pk_bf16_f32 v66, v70, v71
	v_cvt_pk_bf16_f32 v67, v72, v73
	v_cvt_pk_bf16_f32 v68, v68, v69
	v_cvt_pk_bf16_f32 v69, v76, v77
	global_store_dwordx4 v[84:85], v[66:69], off offset:256
	s_nop 1
	v_add_u32_e32 v66, 0x80, v142
	v_ashrrev_i32_e32 v67, 31, v66
	v_lshlrev_b64 v[68:69], 11, v[66:67]
	v_mad_i64_i32 v[66:67], s[22:23], v66, s86, v[144:145]
	v_lshl_add_u64 v[66:67], v[66:67], 0, v[140:141]
	global_load_dwordx2 v[70:71], v[66:67], off
	s_waitcnt vmcnt(0)
	v_cvt_f32_ubyte3_e32 v73, v70
	v_cvt_f32_ubyte2_e32 v72, v70
	v_cvt_f32_ubyte1_e32 v75, v70
	v_cvt_f32_ubyte0_e32 v74, v70
	v_pk_mul_f32 v[74:75], v[74:75], s[72:73] op_sel_hi:[1,0]
	v_pk_mul_f32 v[72:73], v[72:73], s[72:73] op_sel_hi:[1,0]
	v_pk_mul_f32 v[62:63], v[62:63], v[74:75]
	v_pk_mul_f32 v[64:65], v[64:65], v[72:73]
	v_cvt_f32_ubyte3_e32 v73, v71
	v_cvt_f32_ubyte2_e32 v72, v71
	v_cvt_f32_ubyte1_e32 v75, v71
	v_cvt_f32_ubyte0_e32 v74, v71
	v_pk_mul_f32 v[70:71], v[74:75], s[72:73] op_sel_hi:[1,0]
	v_pk_mul_f32 v[72:73], v[72:73], s[72:73] op_sel_hi:[1,0]
	s_nop 0
	v_pk_mul_f32 v[72:73], v[60:61], v[72:73]
	v_pk_mul_f32 v[60:61], v[58:59], v[70:71]
	v_lshl_add_u64 v[58:59], s[10:11], 0, v[68:69]
	v_lshl_add_u64 v[68:69], v[58:59], 0, v[122:123]
	v_cvt_pk_bf16_f32 v58, v62, v63
	v_cvt_pk_bf16_f32 v59, v64, v65
	v_cvt_pk_bf16_f32 v60, v60, v61
	v_cvt_pk_bf16_f32 v61, v72, v73
	global_store_dwordx4 v[68:69], v[58:61], off
	global_load_dwordx2 v[58:59], v[66:67], off offset:128
	s_waitcnt vmcnt(0)
	v_cvt_f32_ubyte1_e32 v63, v58
	v_cvt_f32_ubyte3_e32 v61, v58
	v_cvt_f32_ubyte2_e32 v60, v58
	v_cvt_f32_ubyte0_e32 v62, v58
	v_pk_mul_f32 v[62:63], v[62:63], s[72:73] op_sel_hi:[1,0]
	v_pk_mul_f32 v[60:61], v[60:61], s[72:73] op_sel_hi:[1,0]
	v_pk_mul_f32 v[54:55], v[54:55], v[62:63]
	v_pk_mul_f32 v[56:57], v[56:57], v[60:61]
	v_cvt_f32_ubyte3_e32 v61, v59
	v_cvt_f32_ubyte2_e32 v60, v59
	v_cvt_f32_ubyte1_e32 v63, v59
	v_cvt_f32_ubyte0_e32 v62, v59
	v_pk_mul_f32 v[58:59], v[62:63], s[72:73] op_sel_hi:[1,0]
	v_pk_mul_f32 v[60:61], v[60:61], s[72:73] op_sel_hi:[1,0]
	s_nop 0
	v_pk_mul_f32 v[60:61], v[52:53], v[60:61]
	v_pk_mul_f32 v[52:53], v[50:51], v[58:59]
	v_cvt_pk_bf16_f32 v50, v54, v55
	v_cvt_pk_bf16_f32 v51, v56, v57
	v_cvt_pk_bf16_f32 v52, v52, v53
	v_cvt_pk_bf16_f32 v53, v60, v61
	global_store_dwordx4 v[68:69], v[50:53], off offset:256
	s_nop 1
	v_add_u32_e32 v50, 0x90, v142
	v_ashrrev_i32_e32 v51, 31, v50
	v_lshlrev_b64 v[52:53], 11, v[50:51]
	v_mad_i64_i32 v[50:51], s[22:23], v50, s86, v[144:145]
	v_lshl_add_u64 v[50:51], v[50:51], 0, v[140:141]
	global_load_dwordx2 v[54:55], v[50:51], off
	s_waitcnt vmcnt(0)
; __device__ __forceinline__ unsigned cvtpk(float lo, float hi) { const f32x2_t v = {lo, hi}; const bf16x2_t b = __builtin_convertvector(v, bf16x2_t); return __builtin_bit_cast(unsigned, b); }
; __device__ __forceinline__ float bf_lo(unsigned u) { return __uint_as_float(u << 16); }
; __device__ __forceinline__ float bf_hi(unsigned u) { return __uint_as_float(u & 0xffff0000u); }
;     __device__ __forceinline__ void operator()(const f32x4 (&acc)[2][2][4][2], const pg8::Unit& u, int wr, int wc, int fr, int fq) const {
;         const int row0 = u.pm * 256 + wr * 64 + fr, col0 = u.pn * 256 + wc * 32 + 8 * fq;
; #pragma unroll
;         for (int ai = 0; ai < 2; ++ai)
; #pragma unroll
;             for (int m = 0; m < 4; ++m) {
;                 const size_t r = (size_t)(row0 + ai * 128 + m * 16);
; #pragma unroll
;                 for (int bj = 0; bj < 2; ++bj) {
;                     const int c = col0 + 128 * bj;
;                     const u32x2 g = *(const u32x2*)((const unsigned char*)G + r * 3072 + STEP * 1024 + c);
;                     f32x4 v0 = acc[ai][bj][m][0], v1 = acc[ai][bj][m][1];
;                     constexpr float S8 = 1.f / 255.f;
;                     v0 = v0 * ((f32x4){(float)(g.x & 255u), (float)((g.x >> 8) & 255u), (float)((g.x >> 16) & 255u), (float)(g.x >> 24)} * S8);
;                     v1 = v1 * ((f32x4){(float)(g.y & 255u), (float)((g.y >> 8) & 255u), (float)((g.y >> 16) & 255u), (float)(g.y >> 24)} * S8);
;                     bf16_t* tp = (STEP < 2 ? T : Z) + r * 1024 + c;
;                     if (STEP > 0) { const u32x4 t = *(const u32x4*)(T + r * 1024 + c);
;                         v0 = v0 + (f32x4){bf_lo(t.x), bf_hi(t.x), bf_lo(t.y), bf_hi(t.y)}; v1 = v1 + (f32x4){bf_lo(t.z), bf_hi(t.z), bf_lo(t.w), bf_hi(t.w)}; }
;                     u32x4 w; w.x = cvtpk(v0[0], v0[1]); w.y = cvtpk(v0[2], v0[3]); w.z = cvtpk(v1[0], v1[1]); w.w = cvtpk(v1[2], v1[3]); *(u32x4*)tp = w;
;                 }
	v_cvt_f32_ubyte3_e32 v57, v54
	v_cvt_f32_ubyte2_e32 v56, v54
	v_cvt_f32_ubyte1_e32 v59, v54
	v_cvt_f32_ubyte0_e32 v58, v54
	v_pk_mul_f32 v[58:59], v[58:59], s[72:73] op_sel_hi:[1,0]
	v_pk_mul_f32 v[56:57], v[56:57], s[72:73] op_sel_hi:[1,0]
	v_pk_mul_f32 v[46:47], v[46:47], v[58:59]
	v_pk_mul_f32 v[48:49], v[48:49], v[56:57]
	v_cvt_f32_ubyte3_e32 v57, v55
	v_cvt_f32_ubyte2_e32 v56, v55
	v_cvt_f32_ubyte1_e32 v59, v55
	v_cvt_f32_ubyte0_e32 v58, v55
	v_pk_mul_f32 v[54:55], v[58:59], s[72:73] op_sel_hi:[1,0]
	v_pk_mul_f32 v[56:57], v[56:57], s[72:73] op_sel_hi:[1,0]
	s_nop 0
	v_pk_mul_f32 v[56:57], v[44:45], v[56:57]
	v_pk_mul_f32 v[44:45], v[42:43], v[54:55]
	v_lshl_add_u64 v[42:43], s[10:11], 0, v[52:53]
	v_lshl_add_u64 v[52:53], v[42:43], 0, v[122:123]
	v_cvt_pk_bf16_f32 v42, v46, v47
	v_cvt_pk_bf16_f32 v43, v48, v49
	v_cvt_pk_bf16_f32 v44, v44, v45
	v_cvt_pk_bf16_f32 v45, v56, v57
	global_store_dwordx4 v[52:53], v[42:45], off
	global_load_dwordx2 v[42:43], v[50:51], off offset:128
	s_waitcnt vmcnt(0)
	v_cvt_f32_ubyte1_e32 v47, v42
	v_cvt_f32_ubyte3_e32 v45, v42
	v_cvt_f32_ubyte2_e32 v44, v42
	v_cvt_f32_ubyte0_e32 v46, v42
	v_pk_mul_f32 v[46:47], v[46:47], s[72:73] op_sel_hi:[1,0]
	v_pk_mul_f32 v[44:45], v[44:45], s[72:73] op_sel_hi:[1,0]
	v_pk_mul_f32 v[38:39], v[38:39], v[46:47]
	v_pk_mul_f32 v[40:41], v[40:41], v[44:45]
	v_cvt_f32_ubyte3_e32 v45, v43
	v_cvt_f32_ubyte2_e32 v44, v43
	v_cvt_f32_ubyte1_e32 v47, v43
	v_cvt_f32_ubyte0_e32 v46, v43
	v_pk_mul_f32 v[42:43], v[46:47], s[72:73] op_sel_hi:[1,0]
	v_pk_mul_f32 v[44:45], v[44:45], s[72:73] op_sel_hi:[1,0]
	s_nop 0
	v_pk_mul_f32 v[44:45], v[36:37], v[44:45]
	v_pk_mul_f32 v[36:37], v[34:35], v[42:43]
	v_cvt_pk_bf16_f32 v34, v38, v39
	v_cvt_pk_bf16_f32 v35, v40, v41
	v_cvt_pk_bf16_f32 v36, v36, v37
	v_cvt_pk_bf16_f32 v37, v44, v45
	global_store_dwordx4 v[52:53], v[34:37], off offset:256
	s_nop 1
	v_add_u32_e32 v34, 0xa0, v142
	v_ashrrev_i32_e32 v35, 31, v34
	v_lshlrev_b64 v[36:37], 11, v[34:35]
	v_mad_i64_i32 v[34:35], s[22:23], v34, s86, v[144:145]
	v_lshl_add_u64 v[34:35], v[34:35], 0, v[140:141]
	global_load_dwordx2 v[38:39], v[34:35], off
	s_waitcnt vmcnt(0)
	v_cvt_f32_ubyte3_e32 v41, v38
	v_cvt_f32_ubyte2_e32 v40, v38
	v_cvt_f32_ubyte1_e32 v43, v38
	v_cvt_f32_ubyte0_e32 v42, v38
	v_pk_mul_f32 v[42:43], v[42:43], s[72:73] op_sel_hi:[1,0]
	v_pk_mul_f32 v[40:41], v[40:41], s[72:73] op_sel_hi:[1,0]
	v_pk_mul_f32 v[30:31], v[30:31], v[42:43]
	v_pk_mul_f32 v[32:33], v[32:33], v[40:41]
	v_cvt_f32_ubyte3_e32 v41, v39
	v_cvt_f32_ubyte2_e32 v40, v39
	v_cvt_f32_ubyte1_e32 v43, v39
	v_cvt_f32_ubyte0_e32 v42, v39
	v_pk_mul_f32 v[38:39], v[42:43], s[72:73] op_sel_hi:[1,0]
	v_pk_mul_f32 v[40:41], v[40:41], s[72:73] op_sel_hi:[1,0]
	s_nop 0
	v_pk_mul_f32 v[40:41], v[28:29], v[40:41]
	v_pk_mul_f32 v[28:29], v[26:27], v[38:39]
	v_lshl_add_u64 v[26:27], s[10:11], 0, v[36:37]
	v_lshl_add_u64 v[36:37], v[26:27], 0, v[122:123]
	v_cvt_pk_bf16_f32 v26, v30, v31
	v_cvt_pk_bf16_f32 v27, v32, v33
	v_cvt_pk_bf16_f32 v28, v28, v29
	v_cvt_pk_bf16_f32 v29, v40, v41
	global_store_dwordx4 v[36:37], v[26:29], off
	global_load_dwordx2 v[26:27], v[34:35], off offset:128
	s_waitcnt vmcnt(0)
	v_cvt_f32_ubyte1_e32 v31, v26
	v_cvt_f32_ubyte3_e32 v29, v26
	v_cvt_f32_ubyte2_e32 v28, v26
	v_cvt_f32_ubyte0_e32 v30, v26
	v_pk_mul_f32 v[30:31], v[30:31], s[72:73] op_sel_hi:[1,0]
	v_pk_mul_f32 v[28:29], v[28:29], s[72:73] op_sel_hi:[1,0]
	v_pk_mul_f32 v[22:23], v[22:23], v[30:31]
	v_pk_mul_f32 v[24:25], v[24:25], v[28:29]
	v_cvt_f32_ubyte3_e32 v29, v27
	v_cvt_f32_ubyte2_e32 v28, v27
	v_cvt_f32_ubyte1_e32 v31, v27
	v_cvt_f32_ubyte0_e32 v30, v27
	v_pk_mul_f32 v[26:27], v[30:31], s[72:73] op_sel_hi:[1,0]
	v_pk_mul_f32 v[28:29], v[28:29], s[72:73] op_sel_hi:[1,0]
	s_nop 0
	v_pk_mul_f32 v[28:29], v[20:21], v[28:29]
	v_pk_mul_f32 v[20:21], v[18:19], v[26:27]
	v_cvt_pk_bf16_f32 v18, v22, v23
	v_cvt_pk_bf16_f32 v19, v24, v25
	v_cvt_pk_bf16_f32 v20, v20, v21
	v_cvt_pk_bf16_f32 v21, v28, v29
	global_store_dwordx4 v[36:37], v[18:21], off offset:256
	s_nop 1
	v_add_u32_e32 v18, 0xb0, v142
	v_ashrrev_i32_e32 v19, 31, v18
	v_lshlrev_b64 v[20:21], 11, v[18:19]
	v_mad_i64_i32 v[18:19], s[22:23], v18, s86, v[144:145]
	v_lshl_add_u64 v[18:19], v[18:19], 0, v[140:141]
	global_load_dwordx2 v[22:23], v[18:19], off
	s_mov_b64 s[22:23], -1
	s_waitcnt vmcnt(0)
	v_cvt_f32_ubyte3_e32 v25, v22
	v_cvt_f32_ubyte2_e32 v24, v22
	v_cvt_f32_ubyte1_e32 v27, v22
	v_cvt_f32_ubyte0_e32 v26, v22
	v_pk_mul_f32 v[26:27], v[26:27], s[72:73] op_sel_hi:[1,0]
	v_pk_mul_f32 v[24:25], v[24:25], s[72:73] op_sel_hi:[1,0]
	v_pk_mul_f32 v[14:15], v[14:15], v[26:27]
	v_pk_mul_f32 v[16:17], v[16:17], v[24:25]
	v_cvt_f32_ubyte3_e32 v25, v23
	v_cvt_f32_ubyte2_e32 v24, v23
	v_cvt_f32_ubyte1_e32 v27, v23
	v_cvt_f32_ubyte0_e32 v26, v23
	v_pk_mul_f32 v[22:23], v[26:27], s[72:73] op_sel_hi:[1,0]
	v_pk_mul_f32 v[24:25], v[24:25], s[72:73] op_sel_hi:[1,0]
	s_nop 0
	v_pk_mul_f32 v[24:25], v[12:13], v[24:25]
	v_pk_mul_f32 v[12:13], v[10:11], v[22:23]
	v_lshl_add_u64 v[10:11], s[10:11], 0, v[20:21]
	v_lshl_add_u64 v[20:21], v[10:11], 0, v[122:123]
	v_cvt_pk_bf16_f32 v10, v14, v15
	v_cvt_pk_bf16_f32 v11, v16, v17
	v_cvt_pk_bf16_f32 v12, v12, v13
	v_cvt_pk_bf16_f32 v13, v24, v25
	global_store_dwordx4 v[20:21], v[10:13], off
	global_load_dwordx2 v[10:11], v[18:19], off offset:128
	s_waitcnt vmcnt(0)
	v_cvt_f32_ubyte1_e32 v15, v10
	v_cvt_f32_ubyte3_e32 v13, v10
	v_cvt_f32_ubyte2_e32 v12, v10
	v_cvt_f32_ubyte0_e32 v14, v10
	v_pk_mul_f32 v[14:15], v[14:15], s[72:73] op_sel_hi:[1,0]
	v_pk_mul_f32 v[12:13], v[12:13], s[72:73] op_sel_hi:[1,0]
	v_pk_mul_f32 v[6:7], v[6:7], v[14:15]
	v_pk_mul_f32 v[8:9], v[8:9], v[12:13]
	v_cvt_f32_ubyte3_e32 v13, v11
	v_cvt_f32_ubyte2_e32 v12, v11
	v_cvt_f32_ubyte1_e32 v15, v11
	v_cvt_f32_ubyte0_e32 v14, v11
	v_pk_mul_f32 v[10:11], v[14:15], s[72:73] op_sel_hi:[1,0]
	v_pk_mul_f32 v[12:13], v[12:13], s[72:73] op_sel_hi:[1,0]
	s_nop 0
	v_pk_mul_f32 v[12:13], v[4:5], v[12:13]
	v_pk_mul_f32 v[4:5], v[2:3], v[10:11]
	v_cvt_pk_bf16_f32 v2, v6, v7
	v_cvt_pk_bf16_f32 v3, v8, v9
	v_cvt_pk_bf16_f32 v4, v4, v5
	v_cvt_pk_bf16_f32 v5, v12, v13
	global_store_dwordx4 v[20:21], v[2:5], off offset:256
	s_cmp_lg_u32 s47, 2
	s_cbranch_scc1 .Lmg_wskip0
	s_load_dwordx2 s[30:31], s[68:69], 0xc0
	v_readlane_b32 s32, v255, 2
	s_waitcnt vmcnt(0)
	buffer_wbl2 sc1
	v_mov_b32_e32 v2, s34
	v_mul_u32_u24_e32 v2, 0xaaab, v2
	v_lshrrev_b32_e32 v2, 17, v2
	s_lshl_b32 s32, s32, 4
	v_add_u32_e32 v2, s32, v2
	v_lshlrev_b32_e32 v2, 4, v2
	v_add_u32_e32 v2, 0x7600, v2
	v_mov_b32_e32 v3, 1
	s_waitcnt vmcnt(0) lgkmcnt(0)
	global_atomic_add v2, v3, s[30:31]
.Lmg_wskip0:
	s_cbranch_vccnz .LBB0_507
	s_andn2_b64 vcc, exec, s[6:7]
	s_cbranch_vccnz .LBB0_506
	s_barrier
	s_branch .LBB0_506

;     __host__ __device__ bool next(int i, Unit& u) const {
;         const long L = (long)i * G + c; if (L >= nwg) return false;
;         int wgid = (int)L; { const int q = nwg / NXCD, r = nwg % NXCD, xcd = wgid % NXCD, off = wgid / NXCD; wgid = (xcd < r ? xcd * (q + 1) : r * (q + 1) + (xcd - r) * q) + off; }
;         const int nig = WGM * nN, gid = wgid / nig, fm = gid * WGM, gsz = (nM - fm) < WGM ? (nM - fm) : WGM;
;         u.pm = fm + ((wgid % nig) % gsz); u.pn = (wgid % nig) / gsz; u.koff = 0; u.nt = 0; return true;
.LBB0_524:
	s_add_i32 s48, s48, 1
	s_mul_i32 s1, s34, 0xaaab
	s_lshr_b32 s1, s1, 17
	s_mul_i32 s6, s1, 3
	s_sub_i32 s6, s34, s6
	s_cmp_eq_u32 s6, 1
	s_cselect_b32 s6, 0, 0x10000000
	s_cmp_lt_u32 s34, 24
	s_cselect_b32 s6, s6, 0x10000000
	s_lshl_b32 s18, s48, 8
	s_add_i32 s18, s18, s1
	s_add_i32 s18, s18, s6
	s_mov_b32 s19, 0
	s_cmp_lg_u32 s48, 2
	s_cbranch_scc1 .Lmg_rskip1
	s_load_dwordx2 s[30:31], s[68:69], 0xc0
	v_readlane_b32 s6, v255, 2
	s_lshl_b32 s6, s6, 4
	s_add_i32 s6, s6, s1
	s_lshl_b32 s6, s6, 4
	s_addk_i32 s6, 0x7600
	v_mov_b32_e32 v2, s6
	s_mov_b32 s1, 0
	s_waitcnt lgkmcnt(0)
.Lmg_spin1:
	global_load_dword v3, v2, s[30:31] sc1
	s_waitcnt vmcnt(0)
	v_readfirstlane_b32 s6, v3
	s_cmp_ge_u32 s6, 0x200
	s_cbranch_scc1 .Lmg_done1
	s_sleep 1
	s_add_i32 s1, s1, 1
	s_cmp_lt_u32 s1, 0x4000
	s_cbranch_scc1 .Lmg_spin1
.Lmg_done1:
	buffer_inv sc1
	s_waitcnt vmcnt(0)
.Lmg_rskip1:
	v_mov_b64_e32 v[2:3], s[94:95]
	v_cmp_ge_i64_e32 vcc, s[18:19], v[2:3]
	v_cmp_lt_i64_e64 s[6:7], s[18:19], v[2:3]
	s_cbranch_vccnz .LBB0_526
	s_ashr_i32 s1, s18, 31
	s_lshr_b32 s1, s1, 29
	s_add_i32 s1, s18, s1
	s_ashr_i32 s14, s1, 3
	s_and_b32 s1, s1, -8
	s_sub_i32 s1, s18, s1
	s_cmp_lt_i32 s1, 0
	s_cselect_b32 s15, s42, s40
	s_mul_i32 s1, s15, s1
	s_add_i32 s1, s1, s14
	s_ashr_i32 s14, s1, 31
	s_lshr_b32 s14, s14, 27
	s_add_i32 s14, s1, s14
	s_ashr_i32 s15, s14, 5
	s_lshl_b32 s15, s15, 3
	s_sub_i32 s16, s50, s15
	s_min_i32 s16, s16, 8
	s_abs_i32 s17, s16
	v_cvt_f32_u32_e32 v2, s17
	s_sub_i32 s19, 0, s17
	s_andn2_b32 s14, s14, 31
	s_sub_i32 s1, s1, s14
	v_rcp_iflag_f32_e32 v2, v2
	s_abs_i32 s14, s1
	s_xor_b32 s18, s1, s16
	s_ashr_i32 s18, s18, 31
	v_mul_f32_e32 v2, 0x4f7ffffe, v2
	v_cvt_u32_f32_e32 v2, v2
	s_nop 0
	v_readfirstlane_b32 s20, v2
	s_mul_i32 s19, s19, s20
	s_mul_hi_u32 s19, s20, s19
	s_add_i32 s20, s20, s19
	s_mul_hi_u32 s19, s14, s20
	s_mul_i32 s20, s19, s17
	s_sub_i32 s14, s14, s20
	s_add_i32 s21, s19, 1
	s_sub_i32 s20, s14, s17
	s_cmp_ge_u32 s14, s17
	s_cselect_b32 s19, s21, s19
	s_cselect_b32 s14, s20, s14
	s_add_i32 s20, s19, 1
	s_cmp_ge_u32 s14, s17
	s_cselect_b32 s14, s20, s19
	s_xor_b32 s14, s14, s18
	s_sub_i32 s14, s14, s18
	s_mul_i32 s16, s14, s16
	s_sub_i32 s1, s1, s16
	s_add_i32 s16, s1, s15

; __device__ __forceinline__ unsigned cvtpk(float lo, float hi) { const f32x2_t v = {lo, hi}; const bf16x2_t b = __builtin_convertvector(v, bf16x2_t); return __builtin_bit_cast(unsigned, b); }
; __device__ __forceinline__ float bf_lo(unsigned u) { return __uint_as_float(u << 16); }
; __device__ __forceinline__ float bf_hi(unsigned u) { return __uint_as_float(u & 0xffff0000u); }
;     __device__ __forceinline__ void operator()(const f32x4 (&acc)[2][2][4][2], const pg8::Unit& u, int wr, int wc, int fr, int fq) const {
;         const int row0 = u.pm * 256 + wr * 64 + fr, col0 = u.pn * 256 + wc * 32 + 8 * fq;
; #pragma unroll
;         for (int ai = 0; ai < 2; ++ai)
; #pragma unroll
;             for (int m = 0; m < 4; ++m) {
;                 const size_t r = (size_t)(row0 + ai * 128 + m * 16);
; #pragma unroll
;                 for (int bj = 0; bj < 2; ++bj) {
;                     const int c = col0 + 128 * bj;
;                     const u32x2 g = *(const u32x2*)((const unsigned char*)G + r * 3072 + STEP * 1024 + c);
;                     f32x4 v0 = acc[ai][bj][m][0], v1 = acc[ai][bj][m][1];
;                     constexpr float S8 = 1.f / 255.f;
;                     v0 = v0 * ((f32x4){(float)(g.x & 255u), (float)((g.x >> 8) & 255u), (float)((g.x >> 16) & 255u), (float)(g.x >> 24)} * S8);
;                     v1 = v1 * ((f32x4){(float)(g.y & 255u), (float)((g.y >> 8) & 255u), (float)((g.y >> 16) & 255u), (float)(g.y >> 24)} * S8);
;                     bf16_t* tp = (STEP < 2 ? T : Z) + r * 1024 + c;
;                     if (STEP > 0) { const u32x4 t = *(const u32x4*)(T + r * 1024 + c);
;                         v0 = v0 + (f32x4){bf_lo(t.x), bf_hi(t.x), bf_lo(t.y), bf_hi(t.y)}; v1 = v1 + (f32x4){bf_lo(t.z), bf_hi(t.z), bf_lo(t.w), bf_hi(t.w)}; }
;                     u32x4 w; w.x = cvtpk(v0[0], v0[1]); w.y = cvtpk(v0[2], v0[3]); w.z = cvtpk(v1[0], v1[1]); w.w = cvtpk(v1[2], v1[3]); *(u32x4*)tp = w;
;                 }
.LBB0_530:
	v_lshl_add_u32 v142, s24, 8, v148
	v_lshl_or_b32 v140, s22, 8, v150
	v_mov_b64_e32 v[144:145], s[8:9]
	v_mad_i64_i32 v[152:153], s[22:23], v142, s86, v[144:145]
	v_ashrrev_i32_e32 v141, 31, v140
	v_lshl_add_u64 v[156:157], v[152:153], 0, v[140:141]
	global_load_dwordx2 v[152:153], v[156:157], off offset:1024
	v_ashrrev_i32_e32 v143, 31, v142
	v_lshlrev_b64 v[146:147], 11, v[142:143]
	s_andn2_b64 vcc, exec, s[6:7]
	s_waitcnt vmcnt(0)
	v_cvt_f32_ubyte3_e32 v155, v152
	v_cvt_f32_ubyte2_e32 v154, v152
	v_cvt_f32_ubyte1_e32 v159, v152
	v_cvt_f32_ubyte0_e32 v158, v152
	v_pk_mul_f32 v[160:161], v[154:155], s[72:73] op_sel_hi:[1,0]
	v_cvt_f32_ubyte3_e32 v155, v153
	v_cvt_f32_ubyte2_e32 v154, v153
	v_cvt_f32_ubyte1_e32 v163, v153
	v_cvt_f32_ubyte0_e32 v162, v153
	v_lshl_add_u64 v[152:153], s[10:11], 0, v[146:147]
	v_lshlrev_b64 v[146:147], 1, v[140:141]
	v_lshl_add_u64 v[166:167], v[152:153], 0, v[146:147]
	v_pk_mul_f32 v[164:165], v[154:155], s[72:73] op_sel_hi:[1,0]
	global_load_dwordx4 v[152:155], v[166:167], off
	v_pk_mul_f32 v[158:159], v[158:159], s[72:73] op_sel_hi:[1,0]
	v_pk_mul_f32 v[162:163], v[162:163], s[72:73] op_sel_hi:[1,0]
	s_waitcnt vmcnt(0)
	v_lshlrev_b32_e32 v168, 16, v152
	v_and_b32_e32 v169, 0xffff0000, v152
	v_lshlrev_b32_e32 v152, 16, v153
	v_and_b32_e32 v153, 0xffff0000, v153
	v_pk_fma_f32 v[128:129], v[128:129], v[160:161], v[152:153]
	v_lshlrev_b32_e32 v152, 16, v154
	v_and_b32_e32 v153, 0xffff0000, v154
	v_lshlrev_b32_e32 v154, 16, v155
	v_and_b32_e32 v155, 0xffff0000, v155
	v_pk_fma_f32 v[126:127], v[126:127], v[158:159], v[168:169]
	v_pk_fma_f32 v[154:155], v[124:125], v[164:165], v[154:155]
	v_pk_fma_f32 v[124:125], v[122:123], v[162:163], v[152:153]
	v_cvt_pk_bf16_f32 v122, v126, v127
	v_cvt_pk_bf16_f32 v123, v128, v129
	v_cvt_pk_bf16_f32 v124, v124, v125
	v_cvt_pk_bf16_f32 v125, v154, v155
	global_store_dwordx4 v[166:167], v[122:125], off
	global_load_dwordx2 v[122:123], v[156:157], off offset:1152
	s_waitcnt vmcnt(0)
	v_cvt_f32_ubyte1_e32 v127, v122
	v_cvt_f32_ubyte3_e32 v125, v122
	v_cvt_f32_ubyte2_e32 v124, v122
	v_pk_mul_f32 v[128:129], v[124:125], s[72:73] op_sel_hi:[1,0]
	v_cvt_f32_ubyte3_e32 v125, v123
	v_cvt_f32_ubyte2_e32 v124, v123
	v_cvt_f32_ubyte0_e32 v126, v122
	v_cvt_f32_ubyte1_e32 v153, v123
	v_cvt_f32_ubyte0_e32 v152, v123
	v_pk_mul_f32 v[154:155], v[124:125], s[72:73] op_sel_hi:[1,0]
	global_load_dwordx4 v[122:125], v[166:167], off offset:256
	v_pk_mul_f32 v[126:127], v[126:127], s[72:73] op_sel_hi:[1,0]
	v_pk_mul_f32 v[152:153], v[152:153], s[72:73] op_sel_hi:[1,0]
	s_waitcnt vmcnt(0)
	v_lshlrev_b32_e32 v156, 16, v122
	v_and_b32_e32 v157, 0xffff0000, v122
	v_lshlrev_b32_e32 v122, 16, v123
	v_and_b32_e32 v123, 0xffff0000, v123
	v_pk_fma_f32 v[120:121], v[120:121], v[128:129], v[122:123]
	v_lshlrev_b32_e32 v122, 16, v124
	v_and_b32_e32 v123, 0xffff0000, v124
	v_lshlrev_b32_e32 v124, 16, v125
	v_and_b32_e32 v125, 0xffff0000, v125
	v_pk_fma_f32 v[118:119], v[118:119], v[126:127], v[156:157]
	v_pk_fma_f32 v[124:125], v[116:117], v[154:155], v[124:125]
	v_pk_fma_f32 v[116:117], v[114:115], v[152:153], v[122:123]
	v_cvt_pk_bf16_f32 v114, v118, v119
	v_cvt_pk_bf16_f32 v115, v120, v121
	v_cvt_pk_bf16_f32 v116, v116, v117
	v_cvt_pk_bf16_f32 v117, v124, v125
	global_store_dwordx4 v[166:167], v[114:117], off offset:256
	s_nop 1
	v_or_b32_e32 v114, 16, v142
	v_ashrrev_i32_e32 v115, 31, v114
	v_lshlrev_b64 v[116:117], 11, v[114:115]
	v_mad_i64_i32 v[114:115], s[22:23], v114, s86, v[144:145]
	v_lshl_add_u64 v[120:121], v[114:115], 0, v[140:141]
	global_load_dwordx2 v[114:115], v[120:121], off offset:1024
	s_waitcnt vmcnt(0)
	v_cvt_f32_ubyte3_e32 v119, v114
	v_cvt_f32_ubyte2_e32 v118, v114
	v_cvt_f32_ubyte1_e32 v123, v114
	v_cvt_f32_ubyte0_e32 v122, v114
	v_pk_mul_f32 v[124:125], v[118:119], s[72:73] op_sel_hi:[1,0]
	v_cvt_f32_ubyte3_e32 v119, v115
	v_cvt_f32_ubyte2_e32 v118, v115
	v_cvt_f32_ubyte1_e32 v127, v115
	v_cvt_f32_ubyte0_e32 v126, v115
	v_lshl_add_u64 v[114:115], s[10:11], 0, v[116:117]
	v_lshl_add_u64 v[114:115], v[114:115], 0, v[146:147]
	v_pk_mul_f32 v[128:129], v[118:119], s[72:73] op_sel_hi:[1,0]
	global_load_dwordx4 v[116:119], v[114:115], off
	v_pk_mul_f32 v[122:123], v[122:123], s[72:73] op_sel_hi:[1,0]
	v_pk_mul_f32 v[126:127], v[126:127], s[72:73] op_sel_hi:[1,0]
	s_waitcnt vmcnt(0)
	v_lshlrev_b32_e32 v152, 16, v116
	v_and_b32_e32 v153, 0xffff0000, v116
	v_lshlrev_b32_e32 v116, 16, v117
	v_and_b32_e32 v117, 0xffff0000, v117
	v_pk_fma_f32 v[112:113], v[112:113], v[124:125], v[116:117]
	v_lshlrev_b32_e32 v116, 16, v118
	v_and_b32_e32 v117, 0xffff0000, v118
	v_lshlrev_b32_e32 v118, 16, v119
	v_and_b32_e32 v119, 0xffff0000, v119
	v_pk_fma_f32 v[110:111], v[110:111], v[122:123], v[152:153]
	v_pk_fma_f32 v[118:119], v[108:109], v[128:129], v[118:119]
	v_pk_fma_f32 v[108:109], v[106:107], v[126:127], v[116:117]
	v_cvt_pk_bf16_f32 v106, v110, v111
	v_cvt_pk_bf16_f32 v107, v112, v113
	v_cvt_pk_bf16_f32 v108, v108, v109
	v_cvt_pk_bf16_f32 v109, v118, v119
	global_store_dwordx4 v[114:115], v[106:109], off
	global_load_dwordx2 v[108:109], v[120:121], off offset:1152
	s_waitcnt vmcnt(0)
	v_cvt_f32_ubyte1_e32 v117, v109
	v_cvt_f32_ubyte0_e32 v116, v109
	v_cvt_f32_ubyte3_e32 v111, v108
	v_cvt_f32_ubyte2_e32 v110, v108
	v_cvt_f32_ubyte1_e32 v107, v108
	v_cvt_f32_ubyte0_e32 v106, v108
	v_cvt_f32_ubyte3_e32 v113, v109
	v_cvt_f32_ubyte2_e32 v112, v109
	v_pk_mul_f32 v[108:109], v[116:117], s[72:73] op_sel_hi:[1,0]
	global_load_dwordx4 v[116:119], v[114:115], off offset:256
	v_pk_mul_f32 v[106:107], v[106:107], s[72:73] op_sel_hi:[1,0]
	v_pk_mul_f32 v[110:111], v[110:111], s[72:73] op_sel_hi:[1,0]
	v_pk_mul_f32 v[112:113], v[112:113], s[72:73] op_sel_hi:[1,0]
	s_waitcnt vmcnt(0)
; __device__ __forceinline__ unsigned cvtpk(float lo, float hi) { const f32x2_t v = {lo, hi}; const bf16x2_t b = __builtin_convertvector(v, bf16x2_t); return __builtin_bit_cast(unsigned, b); }
; __device__ __forceinline__ float bf_lo(unsigned u) { return __uint_as_float(u << 16); }
; __device__ __forceinline__ float bf_hi(unsigned u) { return __uint_as_float(u & 0xffff0000u); }
;     __device__ __forceinline__ void operator()(const f32x4 (&acc)[2][2][4][2], const pg8::Unit& u, int wr, int wc, int fr, int fq) const {
;         const int row0 = u.pm * 256 + wr * 64 + fr, col0 = u.pn * 256 + wc * 32 + 8 * fq;
; #pragma unroll
;         for (int ai = 0; ai < 2; ++ai)
; #pragma unroll
;             for (int m = 0; m < 4; ++m) {
;                 const size_t r = (size_t)(row0 + ai * 128 + m * 16);
; #pragma unroll
;                 for (int bj = 0; bj < 2; ++bj) {
;                     const int c = col0 + 128 * bj;
;                     const u32x2 g = *(const u32x2*)((const unsigned char*)G + r * 3072 + STEP * 1024 + c);
;                     f32x4 v0 = acc[ai][bj][m][0], v1 = acc[ai][bj][m][1];
;                     constexpr float S8 = 1.f / 255.f;
;                     v0 = v0 * ((f32x4){(float)(g.x & 255u), (float)((g.x >> 8) & 255u), (float)((g.x >> 16) & 255u), (float)(g.x >> 24)} * S8);
;                     v1 = v1 * ((f32x4){(float)(g.y & 255u), (float)((g.y >> 8) & 255u), (float)((g.y >> 16) & 255u), (float)(g.y >> 24)} * S8);
;                     bf16_t* tp = (STEP < 2 ? T : Z) + r * 1024 + c;
;                     if (STEP > 0) { const u32x4 t = *(const u32x4*)(T + r * 1024 + c);
;                         v0 = v0 + (f32x4){bf_lo(t.x), bf_hi(t.x), bf_lo(t.y), bf_hi(t.y)}; v1 = v1 + (f32x4){bf_lo(t.z), bf_hi(t.z), bf_lo(t.w), bf_hi(t.w)}; }
;                     u32x4 w; w.x = cvtpk(v0[0], v0[1]); w.y = cvtpk(v0[2], v0[3]); w.z = cvtpk(v1[0], v1[1]); w.w = cvtpk(v1[2], v1[3]); *(u32x4*)tp = w;
;                 }
	v_lshlrev_b32_e32 v120, 16, v116
	v_and_b32_e32 v121, 0xffff0000, v116
	v_lshlrev_b32_e32 v116, 16, v117
	v_and_b32_e32 v117, 0xffff0000, v117
	v_pk_fma_f32 v[104:105], v[104:105], v[110:111], v[116:117]
	v_pk_fma_f32 v[102:103], v[102:103], v[106:107], v[120:121]
	v_lshlrev_b32_e32 v106, 16, v118
	v_and_b32_e32 v107, 0xffff0000, v118
	v_lshlrev_b32_e32 v110, 16, v119
	v_and_b32_e32 v111, 0xffff0000, v119
	v_pk_fma_f32 v[110:111], v[100:101], v[112:113], v[110:111]
	v_pk_fma_f32 v[100:101], v[98:99], v[108:109], v[106:107]
	v_cvt_pk_bf16_f32 v98, v102, v103
	v_cvt_pk_bf16_f32 v99, v104, v105
	v_cvt_pk_bf16_f32 v100, v100, v101
	v_cvt_pk_bf16_f32 v101, v110, v111
	global_store_dwordx4 v[114:115], v[98:101], off offset:256
	s_nop 1
	v_or_b32_e32 v98, 32, v142
	v_ashrrev_i32_e32 v99, 31, v98
	v_lshlrev_b64 v[100:101], 11, v[98:99]
	v_mad_i64_i32 v[98:99], s[22:23], v98, s86, v[144:145]
	v_lshl_add_u64 v[104:105], v[98:99], 0, v[140:141]
	global_load_dwordx2 v[98:99], v[104:105], off offset:1024
	s_waitcnt vmcnt(0)
	v_cvt_f32_ubyte3_e32 v103, v98
	v_cvt_f32_ubyte2_e32 v102, v98
	v_cvt_f32_ubyte1_e32 v107, v98
	v_cvt_f32_ubyte0_e32 v106, v98
	v_pk_mul_f32 v[108:109], v[102:103], s[72:73] op_sel_hi:[1,0]
	v_cvt_f32_ubyte3_e32 v103, v99
	v_cvt_f32_ubyte2_e32 v102, v99
	v_cvt_f32_ubyte1_e32 v111, v99
	v_cvt_f32_ubyte0_e32 v110, v99
	v_lshl_add_u64 v[98:99], s[10:11], 0, v[100:101]
	v_lshl_add_u64 v[98:99], v[98:99], 0, v[146:147]
	v_pk_mul_f32 v[112:113], v[102:103], s[72:73] op_sel_hi:[1,0]
	global_load_dwordx4 v[100:103], v[98:99], off
	v_pk_mul_f32 v[106:107], v[106:107], s[72:73] op_sel_hi:[1,0]
	v_pk_mul_f32 v[110:111], v[110:111], s[72:73] op_sel_hi:[1,0]
	s_waitcnt vmcnt(0)
	v_lshlrev_b32_e32 v114, 16, v100
	v_and_b32_e32 v115, 0xffff0000, v100
	v_lshlrev_b32_e32 v100, 16, v101
	v_and_b32_e32 v101, 0xffff0000, v101
	v_pk_fma_f32 v[96:97], v[96:97], v[108:109], v[100:101]
	v_lshlrev_b32_e32 v100, 16, v102
	v_and_b32_e32 v101, 0xffff0000, v102
	v_lshlrev_b32_e32 v102, 16, v103
	v_and_b32_e32 v103, 0xffff0000, v103
	v_pk_fma_f32 v[94:95], v[94:95], v[106:107], v[114:115]
	v_pk_fma_f32 v[102:103], v[92:93], v[112:113], v[102:103]
	v_pk_fma_f32 v[92:93], v[90:91], v[110:111], v[100:101]
	v_cvt_pk_bf16_f32 v90, v94, v95
	v_cvt_pk_bf16_f32 v91, v96, v97
	v_cvt_pk_bf16_f32 v92, v92, v93
	v_cvt_pk_bf16_f32 v93, v102, v103
	global_store_dwordx4 v[98:99], v[90:93], off
	global_load_dwordx2 v[92:93], v[104:105], off offset:1152
	s_waitcnt vmcnt(0)
	v_cvt_f32_ubyte1_e32 v101, v93
	v_cvt_f32_ubyte0_e32 v100, v93
	v_cvt_f32_ubyte3_e32 v95, v92
	v_cvt_f32_ubyte2_e32 v94, v92
	v_cvt_f32_ubyte1_e32 v91, v92
	v_cvt_f32_ubyte0_e32 v90, v92
	v_cvt_f32_ubyte3_e32 v97, v93
	v_cvt_f32_ubyte2_e32 v96, v93
	v_pk_mul_f32 v[92:93], v[100:101], s[72:73] op_sel_hi:[1,0]
	global_load_dwordx4 v[100:103], v[98:99], off offset:256
	v_pk_mul_f32 v[90:91], v[90:91], s[72:73] op_sel_hi:[1,0]
	v_pk_mul_f32 v[94:95], v[94:95], s[72:73] op_sel_hi:[1,0]
	v_pk_mul_f32 v[96:97], v[96:97], s[72:73] op_sel_hi:[1,0]
	s_waitcnt vmcnt(0)
	v_lshlrev_b32_e32 v104, 16, v100
	v_and_b32_e32 v105, 0xffff0000, v100
	v_lshlrev_b32_e32 v100, 16, v101
	v_and_b32_e32 v101, 0xffff0000, v101
	v_pk_fma_f32 v[88:89], v[88:89], v[94:95], v[100:101]
	v_pk_fma_f32 v[86:87], v[86:87], v[90:91], v[104:105]
	v_lshlrev_b32_e32 v90, 16, v102
	v_and_b32_e32 v91, 0xffff0000, v102
	v_lshlrev_b32_e32 v94, 16, v103
	v_and_b32_e32 v95, 0xffff0000, v103
	v_pk_fma_f32 v[94:95], v[84:85], v[96:97], v[94:95]
	v_pk_fma_f32 v[84:85], v[82:83], v[92:93], v[90:91]
	v_cvt_pk_bf16_f32 v82, v86, v87
	v_cvt_pk_bf16_f32 v83, v88, v89
	v_cvt_pk_bf16_f32 v84, v84, v85
	v_cvt_pk_bf16_f32 v85, v94, v95
	global_store_dwordx4 v[98:99], v[82:85], off offset:256
	s_nop 1
	v_or_b32_e32 v82, 48, v142
	v_ashrrev_i32_e32 v83, 31, v82
	v_lshlrev_b64 v[84:85], 11, v[82:83]
	v_mad_i64_i32 v[82:83], s[22:23], v82, s86, v[144:145]
	v_lshl_add_u64 v[88:89], v[82:83], 0, v[140:141]
	global_load_dwordx2 v[82:83], v[88:89], off offset:1024
	s_waitcnt vmcnt(0)
	v_cvt_f32_ubyte3_e32 v87, v82
	v_cvt_f32_ubyte2_e32 v86, v82
	v_cvt_f32_ubyte1_e32 v91, v82
	v_cvt_f32_ubyte0_e32 v90, v82
	v_pk_mul_f32 v[92:93], v[86:87], s[72:73] op_sel_hi:[1,0]
	v_cvt_f32_ubyte3_e32 v87, v83
	v_cvt_f32_ubyte2_e32 v86, v83
	v_cvt_f32_ubyte1_e32 v95, v83
	v_cvt_f32_ubyte0_e32 v94, v83
	v_lshl_add_u64 v[82:83], s[10:11], 0, v[84:85]
	v_lshl_add_u64 v[82:83], v[82:83], 0, v[146:147]
	v_pk_mul_f32 v[96:97], v[86:87], s[72:73] op_sel_hi:[1,0]
	global_load_dwordx4 v[84:87], v[82:83], off
	v_pk_mul_f32 v[90:91], v[90:91], s[72:73] op_sel_hi:[1,0]
	v_pk_mul_f32 v[94:95], v[94:95], s[72:73] op_sel_hi:[1,0]
	s_waitcnt vmcnt(0)
	v_lshlrev_b32_e32 v98, 16, v84
	v_and_b32_e32 v99, 0xffff0000, v84
	v_lshlrev_b32_e32 v84, 16, v85
	v_and_b32_e32 v85, 0xffff0000, v85
	v_pk_fma_f32 v[80:81], v[80:81], v[92:93], v[84:85]
	v_lshlrev_b32_e32 v84, 16, v86
	v_and_b32_e32 v85, 0xffff0000, v86
	v_lshlrev_b32_e32 v86, 16, v87
	v_and_b32_e32 v87, 0xffff0000, v87
	v_pk_fma_f32 v[78:79], v[78:79], v[90:91], v[98:99]
	v_pk_fma_f32 v[86:87], v[76:77], v[96:97], v[86:87]
	v_pk_fma_f32 v[76:77], v[74:75], v[94:95], v[84:85]
	v_cvt_pk_bf16_f32 v74, v78, v79
	v_cvt_pk_bf16_f32 v75, v80, v81
	v_cvt_pk_bf16_f32 v76, v76, v77
	v_cvt_pk_bf16_f32 v77, v86, v87
	global_store_dwordx4 v[82:83], v[74:77], off
	global_load_dwordx2 v[76:77], v[88:89], off offset:1152
	s_waitcnt vmcnt(0)
; __device__ __forceinline__ unsigned cvtpk(float lo, float hi) { const f32x2_t v = {lo, hi}; const bf16x2_t b = __builtin_convertvector(v, bf16x2_t); return __builtin_bit_cast(unsigned, b); }
; __device__ __forceinline__ float bf_lo(unsigned u) { return __uint_as_float(u << 16); }
; __device__ __forceinline__ float bf_hi(unsigned u) { return __uint_as_float(u & 0xffff0000u); }
;     __device__ __forceinline__ void operator()(const f32x4 (&acc)[2][2][4][2], const pg8::Unit& u, int wr, int wc, int fr, int fq) const {
;         const int row0 = u.pm * 256 + wr * 64 + fr, col0 = u.pn * 256 + wc * 32 + 8 * fq;
; #pragma unroll
;         for (int ai = 0; ai < 2; ++ai)
; #pragma unroll
;             for (int m = 0; m < 4; ++m) {
;                 const size_t r = (size_t)(row0 + ai * 128 + m * 16);
; #pragma unroll
;                 for (int bj = 0; bj < 2; ++bj) {
;                     const int c = col0 + 128 * bj;
;                     const u32x2 g = *(const u32x2*)((const unsigned char*)G + r * 3072 + STEP * 1024 + c);
;                     f32x4 v0 = acc[ai][bj][m][0], v1 = acc[ai][bj][m][1];
;                     constexpr float S8 = 1.f / 255.f;
;                     v0 = v0 * ((f32x4){(float)(g.x & 255u), (float)((g.x >> 8) & 255u), (float)((g.x >> 16) & 255u), (float)(g.x >> 24)} * S8);
;                     v1 = v1 * ((f32x4){(float)(g.y & 255u), (float)((g.y >> 8) & 255u), (float)((g.y >> 16) & 255u), (float)(g.y >> 24)} * S8);
;                     bf16_t* tp = (STEP < 2 ? T : Z) + r * 1024 + c;
;                     if (STEP > 0) { const u32x4 t = *(const u32x4*)(T + r * 1024 + c);
;                         v0 = v0 + (f32x4){bf_lo(t.x), bf_hi(t.x), bf_lo(t.y), bf_hi(t.y)}; v1 = v1 + (f32x4){bf_lo(t.z), bf_hi(t.z), bf_lo(t.w), bf_hi(t.w)}; }
;                     u32x4 w; w.x = cvtpk(v0[0], v0[1]); w.y = cvtpk(v0[2], v0[3]); w.z = cvtpk(v1[0], v1[1]); w.w = cvtpk(v1[2], v1[3]); *(u32x4*)tp = w;
;                 }
	v_cvt_f32_ubyte1_e32 v85, v77
	v_cvt_f32_ubyte0_e32 v84, v77
	v_cvt_f32_ubyte3_e32 v79, v76
	v_cvt_f32_ubyte2_e32 v78, v76
	v_cvt_f32_ubyte1_e32 v75, v76
	v_cvt_f32_ubyte0_e32 v74, v76
	v_cvt_f32_ubyte3_e32 v81, v77
	v_cvt_f32_ubyte2_e32 v80, v77
	v_pk_mul_f32 v[76:77], v[84:85], s[72:73] op_sel_hi:[1,0]
	global_load_dwordx4 v[84:87], v[82:83], off offset:256
	v_pk_mul_f32 v[74:75], v[74:75], s[72:73] op_sel_hi:[1,0]
	v_pk_mul_f32 v[78:79], v[78:79], s[72:73] op_sel_hi:[1,0]
	v_pk_mul_f32 v[80:81], v[80:81], s[72:73] op_sel_hi:[1,0]
	s_waitcnt vmcnt(0)
	v_lshlrev_b32_e32 v88, 16, v84
	v_and_b32_e32 v89, 0xffff0000, v84
	v_lshlrev_b32_e32 v84, 16, v85
	v_and_b32_e32 v85, 0xffff0000, v85
	v_pk_fma_f32 v[72:73], v[72:73], v[78:79], v[84:85]
	v_pk_fma_f32 v[70:71], v[70:71], v[74:75], v[88:89]
	v_lshlrev_b32_e32 v74, 16, v86
	v_and_b32_e32 v75, 0xffff0000, v86
	v_lshlrev_b32_e32 v78, 16, v87
	v_and_b32_e32 v79, 0xffff0000, v87
	v_pk_fma_f32 v[78:79], v[68:69], v[80:81], v[78:79]
	v_pk_fma_f32 v[68:69], v[66:67], v[76:77], v[74:75]
	v_cvt_pk_bf16_f32 v66, v70, v71
	v_cvt_pk_bf16_f32 v67, v72, v73
	v_cvt_pk_bf16_f32 v68, v68, v69
	v_cvt_pk_bf16_f32 v69, v78, v79
	global_store_dwordx4 v[82:83], v[66:69], off offset:256
	s_nop 1
	v_add_u32_e32 v66, 0x80, v142
	v_ashrrev_i32_e32 v67, 31, v66
	v_lshlrev_b64 v[68:69], 11, v[66:67]
	v_mad_i64_i32 v[66:67], s[22:23], v66, s86, v[144:145]
	v_lshl_add_u64 v[72:73], v[66:67], 0, v[140:141]
	global_load_dwordx2 v[66:67], v[72:73], off offset:1024
	s_waitcnt vmcnt(0)
	v_cvt_f32_ubyte3_e32 v71, v66
	v_cvt_f32_ubyte2_e32 v70, v66
	v_cvt_f32_ubyte1_e32 v75, v66
	v_cvt_f32_ubyte0_e32 v74, v66
	v_pk_mul_f32 v[76:77], v[70:71], s[72:73] op_sel_hi:[1,0]
	v_cvt_f32_ubyte3_e32 v71, v67
	v_cvt_f32_ubyte2_e32 v70, v67
	v_cvt_f32_ubyte1_e32 v79, v67
	v_cvt_f32_ubyte0_e32 v78, v67
	v_lshl_add_u64 v[66:67], s[10:11], 0, v[68:69]
	v_lshl_add_u64 v[66:67], v[66:67], 0, v[146:147]
	v_pk_mul_f32 v[80:81], v[70:71], s[72:73] op_sel_hi:[1,0]
	global_load_dwordx4 v[68:71], v[66:67], off
	v_pk_mul_f32 v[74:75], v[74:75], s[72:73] op_sel_hi:[1,0]
	v_pk_mul_f32 v[78:79], v[78:79], s[72:73] op_sel_hi:[1,0]
	s_waitcnt vmcnt(0)
	v_lshlrev_b32_e32 v82, 16, v68
	v_and_b32_e32 v83, 0xffff0000, v68
	v_lshlrev_b32_e32 v68, 16, v69
	v_and_b32_e32 v69, 0xffff0000, v69
	v_pk_fma_f32 v[64:65], v[64:65], v[76:77], v[68:69]
	v_lshlrev_b32_e32 v68, 16, v70
	v_and_b32_e32 v69, 0xffff0000, v70
	v_lshlrev_b32_e32 v70, 16, v71
	v_and_b32_e32 v71, 0xffff0000, v71
	v_pk_fma_f32 v[62:63], v[62:63], v[74:75], v[82:83]
	v_pk_fma_f32 v[70:71], v[60:61], v[80:81], v[70:71]
	v_pk_fma_f32 v[60:61], v[58:59], v[78:79], v[68:69]
	v_cvt_pk_bf16_f32 v58, v62, v63
	v_cvt_pk_bf16_f32 v59, v64, v65
	v_cvt_pk_bf16_f32 v60, v60, v61
	v_cvt_pk_bf16_f32 v61, v70, v71
	global_store_dwordx4 v[66:67], v[58:61], off
	global_load_dwordx2 v[60:61], v[72:73], off offset:1152
	s_waitcnt vmcnt(0)
	v_cvt_f32_ubyte1_e32 v69, v61
	v_cvt_f32_ubyte0_e32 v68, v61
	v_cvt_f32_ubyte3_e32 v63, v60
	v_cvt_f32_ubyte2_e32 v62, v60
	v_cvt_f32_ubyte1_e32 v59, v60
	v_cvt_f32_ubyte0_e32 v58, v60
	v_cvt_f32_ubyte3_e32 v65, v61
	v_cvt_f32_ubyte2_e32 v64, v61
	v_pk_mul_f32 v[60:61], v[68:69], s[72:73] op_sel_hi:[1,0]
	global_load_dwordx4 v[68:71], v[66:67], off offset:256
	v_pk_mul_f32 v[58:59], v[58:59], s[72:73] op_sel_hi:[1,0]
	v_pk_mul_f32 v[62:63], v[62:63], s[72:73] op_sel_hi:[1,0]
	v_pk_mul_f32 v[64:65], v[64:65], s[72:73] op_sel_hi:[1,0]
	s_waitcnt vmcnt(0)
	v_lshlrev_b32_e32 v72, 16, v68
	v_and_b32_e32 v73, 0xffff0000, v68
	v_lshlrev_b32_e32 v68, 16, v69
	v_and_b32_e32 v69, 0xffff0000, v69
	v_pk_fma_f32 v[56:57], v[56:57], v[62:63], v[68:69]
	v_pk_fma_f32 v[54:55], v[54:55], v[58:59], v[72:73]
	v_lshlrev_b32_e32 v58, 16, v70
	v_and_b32_e32 v59, 0xffff0000, v70
	v_lshlrev_b32_e32 v62, 16, v71
	v_and_b32_e32 v63, 0xffff0000, v71
	v_pk_fma_f32 v[62:63], v[52:53], v[64:65], v[62:63]
	v_pk_fma_f32 v[52:53], v[50:51], v[60:61], v[58:59]
	v_cvt_pk_bf16_f32 v50, v54, v55
	v_cvt_pk_bf16_f32 v51, v56, v57
	v_cvt_pk_bf16_f32 v52, v52, v53
	v_cvt_pk_bf16_f32 v53, v62, v63
	global_store_dwordx4 v[66:67], v[50:53], off offset:256
	s_nop 1
	v_add_u32_e32 v50, 0x90, v142
	v_ashrrev_i32_e32 v51, 31, v50
	v_lshlrev_b64 v[52:53], 11, v[50:51]
	v_mad_i64_i32 v[50:51], s[22:23], v50, s86, v[144:145]
	v_lshl_add_u64 v[56:57], v[50:51], 0, v[140:141]
	global_load_dwordx2 v[50:51], v[56:57], off offset:1024
	s_waitcnt vmcnt(0)
	v_cvt_f32_ubyte3_e32 v55, v50
	v_cvt_f32_ubyte2_e32 v54, v50
	v_cvt_f32_ubyte1_e32 v59, v50
	v_cvt_f32_ubyte0_e32 v58, v50
	v_pk_mul_f32 v[60:61], v[54:55], s[72:73] op_sel_hi:[1,0]
	v_cvt_f32_ubyte3_e32 v55, v51
	v_cvt_f32_ubyte2_e32 v54, v51
	v_cvt_f32_ubyte1_e32 v63, v51
	v_cvt_f32_ubyte0_e32 v62, v51
	v_lshl_add_u64 v[50:51], s[10:11], 0, v[52:53]
	v_lshl_add_u64 v[50:51], v[50:51], 0, v[146:147]
	v_pk_mul_f32 v[64:65], v[54:55], s[72:73] op_sel_hi:[1,0]
	global_load_dwordx4 v[52:55], v[50:51], off
	v_pk_mul_f32 v[58:59], v[58:59], s[72:73] op_sel_hi:[1,0]
	v_pk_mul_f32 v[62:63], v[62:63], s[72:73] op_sel_hi:[1,0]
	s_waitcnt vmcnt(0)
	v_lshlrev_b32_e32 v66, 16, v52
	v_and_b32_e32 v67, 0xffff0000, v52
	v_lshlrev_b32_e32 v52, 16, v53
	v_and_b32_e32 v53, 0xffff0000, v53
	v_pk_fma_f32 v[48:49], v[48:49], v[60:61], v[52:53]
	v_lshlrev_b32_e32 v52, 16, v54
	v_and_b32_e32 v53, 0xffff0000, v54
	v_lshlrev_b32_e32 v54, 16, v55
	v_and_b32_e32 v55, 0xffff0000, v55
	v_pk_fma_f32 v[46:47], v[46:47], v[58:59], v[66:67]
	v_pk_fma_f32 v[54:55], v[44:45], v[64:65], v[54:55]
	v_pk_fma_f32 v[44:45], v[42:43], v[62:63], v[52:53]
	v_cvt_pk_bf16_f32 v42, v46, v47
	v_cvt_pk_bf16_f32 v43, v48, v49
	v_cvt_pk_bf16_f32 v44, v44, v45
	v_cvt_pk_bf16_f32 v45, v54, v55
	global_store_dwordx4 v[50:51], v[42:45], off
	global_load_dwordx2 v[44:45], v[56:57], off offset:1152
	s_waitcnt vmcnt(0)
; __device__ __forceinline__ unsigned cvtpk(float lo, float hi) { const f32x2_t v = {lo, hi}; const bf16x2_t b = __builtin_convertvector(v, bf16x2_t); return __builtin_bit_cast(unsigned, b); }
; __device__ __forceinline__ float bf_lo(unsigned u) { return __uint_as_float(u << 16); }
; __device__ __forceinline__ float bf_hi(unsigned u) { return __uint_as_float(u & 0xffff0000u); }
;     __device__ __forceinline__ void operator()(const f32x4 (&acc)[2][2][4][2], const pg8::Unit& u, int wr, int wc, int fr, int fq) const {
;         const int row0 = u.pm * 256 + wr * 64 + fr, col0 = u.pn * 256 + wc * 32 + 8 * fq;
; #pragma unroll
;         for (int ai = 0; ai < 2; ++ai)
; #pragma unroll
;             for (int m = 0; m < 4; ++m) {
;                 const size_t r = (size_t)(row0 + ai * 128 + m * 16);
; #pragma unroll
;                 for (int bj = 0; bj < 2; ++bj) {
;                     const int c = col0 + 128 * bj;
;                     const u32x2 g = *(const u32x2*)((const unsigned char*)G + r * 3072 + STEP * 1024 + c);
;                     f32x4 v0 = acc[ai][bj][m][0], v1 = acc[ai][bj][m][1];
;                     constexpr float S8 = 1.f / 255.f;
;                     v0 = v0 * ((f32x4){(float)(g.x & 255u), (float)((g.x >> 8) & 255u), (float)((g.x >> 16) & 255u), (float)(g.x >> 24)} * S8);
;                     v1 = v1 * ((f32x4){(float)(g.y & 255u), (float)((g.y >> 8) & 255u), (float)((g.y >> 16) & 255u), (float)(g.y >> 24)} * S8);
;                     bf16_t* tp = (STEP < 2 ? T : Z) + r * 1024 + c;
;                     if (STEP > 0) { const u32x4 t = *(const u32x4*)(T + r * 1024 + c);
;                         v0 = v0 + (f32x4){bf_lo(t.x), bf_hi(t.x), bf_lo(t.y), bf_hi(t.y)}; v1 = v1 + (f32x4){bf_lo(t.z), bf_hi(t.z), bf_lo(t.w), bf_hi(t.w)}; }
;                     u32x4 w; w.x = cvtpk(v0[0], v0[1]); w.y = cvtpk(v0[2], v0[3]); w.z = cvtpk(v1[0], v1[1]); w.w = cvtpk(v1[2], v1[3]); *(u32x4*)tp = w;
;                 }
	v_cvt_f32_ubyte1_e32 v53, v45
	v_cvt_f32_ubyte0_e32 v52, v45
	v_cvt_f32_ubyte3_e32 v47, v44
	v_cvt_f32_ubyte2_e32 v46, v44
	v_cvt_f32_ubyte1_e32 v43, v44
	v_cvt_f32_ubyte0_e32 v42, v44
	v_cvt_f32_ubyte3_e32 v49, v45
	v_cvt_f32_ubyte2_e32 v48, v45
	v_pk_mul_f32 v[44:45], v[52:53], s[72:73] op_sel_hi:[1,0]
	global_load_dwordx4 v[52:55], v[50:51], off offset:256
	v_pk_mul_f32 v[42:43], v[42:43], s[72:73] op_sel_hi:[1,0]
	v_pk_mul_f32 v[46:47], v[46:47], s[72:73] op_sel_hi:[1,0]
	v_pk_mul_f32 v[48:49], v[48:49], s[72:73] op_sel_hi:[1,0]
	s_waitcnt vmcnt(0)
	v_lshlrev_b32_e32 v56, 16, v52
	v_and_b32_e32 v57, 0xffff0000, v52
	v_lshlrev_b32_e32 v52, 16, v53
	v_and_b32_e32 v53, 0xffff0000, v53
	v_pk_fma_f32 v[40:41], v[40:41], v[46:47], v[52:53]
	v_pk_fma_f32 v[38:39], v[38:39], v[42:43], v[56:57]
	v_lshlrev_b32_e32 v42, 16, v54
	v_and_b32_e32 v43, 0xffff0000, v54
	v_lshlrev_b32_e32 v46, 16, v55
	v_and_b32_e32 v47, 0xffff0000, v55
	v_pk_fma_f32 v[46:47], v[36:37], v[48:49], v[46:47]
	v_pk_fma_f32 v[36:37], v[34:35], v[44:45], v[42:43]
	v_cvt_pk_bf16_f32 v34, v38, v39
	v_cvt_pk_bf16_f32 v35, v40, v41
	v_cvt_pk_bf16_f32 v36, v36, v37
	v_cvt_pk_bf16_f32 v37, v46, v47
	global_store_dwordx4 v[50:51], v[34:37], off offset:256
	s_nop 1
	v_add_u32_e32 v34, 0xa0, v142
	v_ashrrev_i32_e32 v35, 31, v34
	v_lshlrev_b64 v[36:37], 11, v[34:35]
	v_mad_i64_i32 v[34:35], s[22:23], v34, s86, v[144:145]
	v_lshl_add_u64 v[40:41], v[34:35], 0, v[140:141]
	global_load_dwordx2 v[34:35], v[40:41], off offset:1024
	s_waitcnt vmcnt(0)
	v_cvt_f32_ubyte3_e32 v39, v34
	v_cvt_f32_ubyte2_e32 v38, v34
	v_cvt_f32_ubyte1_e32 v43, v34
	v_cvt_f32_ubyte0_e32 v42, v34
	v_pk_mul_f32 v[44:45], v[38:39], s[72:73] op_sel_hi:[1,0]
	v_cvt_f32_ubyte3_e32 v39, v35
	v_cvt_f32_ubyte2_e32 v38, v35
	v_cvt_f32_ubyte1_e32 v47, v35
	v_cvt_f32_ubyte0_e32 v46, v35
	v_lshl_add_u64 v[34:35], s[10:11], 0, v[36:37]
	v_lshl_add_u64 v[34:35], v[34:35], 0, v[146:147]
	v_pk_mul_f32 v[48:49], v[38:39], s[72:73] op_sel_hi:[1,0]
	global_load_dwordx4 v[36:39], v[34:35], off
	v_pk_mul_f32 v[42:43], v[42:43], s[72:73] op_sel_hi:[1,0]
	v_pk_mul_f32 v[46:47], v[46:47], s[72:73] op_sel_hi:[1,0]
	s_waitcnt vmcnt(0)
	v_lshlrev_b32_e32 v50, 16, v36
	v_and_b32_e32 v51, 0xffff0000, v36
	v_lshlrev_b32_e32 v36, 16, v37
	v_and_b32_e32 v37, 0xffff0000, v37
	v_pk_fma_f32 v[32:33], v[32:33], v[44:45], v[36:37]
	v_lshlrev_b32_e32 v36, 16, v38
	v_and_b32_e32 v37, 0xffff0000, v38
	v_lshlrev_b32_e32 v38, 16, v39
	v_and_b32_e32 v39, 0xffff0000, v39
	v_pk_fma_f32 v[30:31], v[30:31], v[42:43], v[50:51]
	v_pk_fma_f32 v[38:39], v[28:29], v[48:49], v[38:39]
	v_pk_fma_f32 v[28:29], v[26:27], v[46:47], v[36:37]
	v_cvt_pk_bf16_f32 v26, v30, v31
	v_cvt_pk_bf16_f32 v27, v32, v33
	v_cvt_pk_bf16_f32 v28, v28, v29
	v_cvt_pk_bf16_f32 v29, v38, v39
	global_store_dwordx4 v[34:35], v[26:29], off
	global_load_dwordx2 v[28:29], v[40:41], off offset:1152
	s_waitcnt vmcnt(0)
	v_cvt_f32_ubyte1_e32 v37, v29
	v_cvt_f32_ubyte0_e32 v36, v29
	v_cvt_f32_ubyte3_e32 v31, v28
	v_cvt_f32_ubyte2_e32 v30, v28
	v_cvt_f32_ubyte1_e32 v27, v28
	v_cvt_f32_ubyte0_e32 v26, v28
	v_cvt_f32_ubyte3_e32 v33, v29
	v_cvt_f32_ubyte2_e32 v32, v29
	v_pk_mul_f32 v[28:29], v[36:37], s[72:73] op_sel_hi:[1,0]
	global_load_dwordx4 v[36:39], v[34:35], off offset:256
	v_pk_mul_f32 v[26:27], v[26:27], s[72:73] op_sel_hi:[1,0]
	v_pk_mul_f32 v[30:31], v[30:31], s[72:73] op_sel_hi:[1,0]
	v_pk_mul_f32 v[32:33], v[32:33], s[72:73] op_sel_hi:[1,0]
	s_waitcnt vmcnt(0)
; __device__ __forceinline__ unsigned cvtpk(float lo, float hi) { const f32x2_t v = {lo, hi}; const bf16x2_t b = __builtin_convertvector(v, bf16x2_t); return __builtin_bit_cast(unsigned, b); }
; __device__ __forceinline__ float bf_lo(unsigned u) { return __uint_as_float(u << 16); }
; __device__ __forceinline__ float bf_hi(unsigned u) { return __uint_as_float(u & 0xffff0000u); }
;     __device__ __forceinline__ void operator()(const f32x4 (&acc)[2][2][4][2], const pg8::Unit& u, int wr, int wc, int fr, int fq) const {
;         const int row0 = u.pm * 256 + wr * 64 + fr, col0 = u.pn * 256 + wc * 32 + 8 * fq;
; #pragma unroll
;         for (int ai = 0; ai < 2; ++ai)
; #pragma unroll
;             for (int m = 0; m < 4; ++m) {
;                 const size_t r = (size_t)(row0 + ai * 128 + m * 16);
; #pragma unroll
;                 for (int bj = 0; bj < 2; ++bj) {
;                     const int c = col0 + 128 * bj;
;                     const u32x2 g = *(const u32x2*)((const unsigned char*)G + r * 3072 + STEP * 1024 + c);
;                     f32x4 v0 = acc[ai][bj][m][0], v1 = acc[ai][bj][m][1];
;                     constexpr float S8 = 1.f / 255.f;
;                     v0 = v0 * ((f32x4){(float)(g.x & 255u), (float)((g.x >> 8) & 255u), (float)((g.x >> 16) & 255u), (float)(g.x >> 24)} * S8);
;                     v1 = v1 * ((f32x4){(float)(g.y & 255u), (float)((g.y >> 8) & 255u), (float)((g.y >> 16) & 255u), (float)(g.y >> 24)} * S8);
;                     bf16_t* tp = (STEP < 2 ? T : Z) + r * 1024 + c;
;                     if (STEP > 0) { const u32x4 t = *(const u32x4*)(T + r * 1024 + c);
;                         v0 = v0 + (f32x4){bf_lo(t.x), bf_hi(t.x), bf_lo(t.y), bf_hi(t.y)}; v1 = v1 + (f32x4){bf_lo(t.z), bf_hi(t.z), bf_lo(t.w), bf_hi(t.w)}; }
;                     u32x4 w; w.x = cvtpk(v0[0], v0[1]); w.y = cvtpk(v0[2], v0[3]); w.z = cvtpk(v1[0], v1[1]); w.w = cvtpk(v1[2], v1[3]); *(u32x4*)tp = w;
;                 }
	v_lshlrev_b32_e32 v40, 16, v36
	v_and_b32_e32 v41, 0xffff0000, v36
	v_lshlrev_b32_e32 v36, 16, v37
	v_and_b32_e32 v37, 0xffff0000, v37
	v_pk_fma_f32 v[24:25], v[24:25], v[30:31], v[36:37]
	v_pk_fma_f32 v[22:23], v[22:23], v[26:27], v[40:41]
	v_lshlrev_b32_e32 v26, 16, v38
	v_and_b32_e32 v27, 0xffff0000, v38
	v_lshlrev_b32_e32 v30, 16, v39
	v_and_b32_e32 v31, 0xffff0000, v39
	v_pk_fma_f32 v[30:31], v[20:21], v[32:33], v[30:31]
	v_pk_fma_f32 v[20:21], v[18:19], v[28:29], v[26:27]
	v_cvt_pk_bf16_f32 v18, v22, v23
	v_cvt_pk_bf16_f32 v19, v24, v25
	v_cvt_pk_bf16_f32 v20, v20, v21
	v_cvt_pk_bf16_f32 v21, v30, v31
	global_store_dwordx4 v[34:35], v[18:21], off offset:256
	s_nop 1
	v_add_u32_e32 v18, 0xb0, v142
	v_ashrrev_i32_e32 v19, 31, v18
	v_lshlrev_b64 v[20:21], 11, v[18:19]
	v_mad_i64_i32 v[18:19], s[22:23], v18, s86, v[144:145]
	v_lshl_add_u64 v[24:25], v[18:19], 0, v[140:141]
	global_load_dwordx2 v[18:19], v[24:25], off offset:1024
	s_mov_b64 s[22:23], -1
	s_waitcnt vmcnt(0)
	v_cvt_f32_ubyte3_e32 v23, v18
	v_cvt_f32_ubyte2_e32 v22, v18
	v_cvt_f32_ubyte1_e32 v27, v18
	v_cvt_f32_ubyte0_e32 v26, v18
	v_pk_mul_f32 v[28:29], v[22:23], s[72:73] op_sel_hi:[1,0]
	v_cvt_f32_ubyte3_e32 v23, v19
	v_cvt_f32_ubyte2_e32 v22, v19
	v_cvt_f32_ubyte1_e32 v31, v19
	v_cvt_f32_ubyte0_e32 v30, v19
	v_lshl_add_u64 v[18:19], s[10:11], 0, v[20:21]
	v_lshl_add_u64 v[18:19], v[18:19], 0, v[146:147]
	v_pk_mul_f32 v[32:33], v[22:23], s[72:73] op_sel_hi:[1,0]
	global_load_dwordx4 v[20:23], v[18:19], off
	v_pk_mul_f32 v[26:27], v[26:27], s[72:73] op_sel_hi:[1,0]
	v_pk_mul_f32 v[30:31], v[30:31], s[72:73] op_sel_hi:[1,0]
	s_waitcnt vmcnt(0)
	v_lshlrev_b32_e32 v34, 16, v20
	v_and_b32_e32 v35, 0xffff0000, v20
	v_lshlrev_b32_e32 v20, 16, v21
	v_and_b32_e32 v21, 0xffff0000, v21
	v_pk_fma_f32 v[16:17], v[16:17], v[28:29], v[20:21]
	v_lshlrev_b32_e32 v20, 16, v22
	v_and_b32_e32 v21, 0xffff0000, v22
	v_lshlrev_b32_e32 v22, 16, v23
	v_and_b32_e32 v23, 0xffff0000, v23
	v_pk_fma_f32 v[14:15], v[14:15], v[26:27], v[34:35]
	v_pk_fma_f32 v[22:23], v[12:13], v[32:33], v[22:23]
	v_pk_fma_f32 v[12:13], v[10:11], v[30:31], v[20:21]
	v_cvt_pk_bf16_f32 v10, v14, v15
	v_cvt_pk_bf16_f32 v11, v16, v17
	v_cvt_pk_bf16_f32 v12, v12, v13
	v_cvt_pk_bf16_f32 v13, v22, v23
	global_store_dwordx4 v[18:19], v[10:13], off
	global_load_dwordx2 v[12:13], v[24:25], off offset:1152
	s_waitcnt vmcnt(0)
	v_cvt_f32_ubyte1_e32 v21, v13
	v_cvt_f32_ubyte0_e32 v20, v13
	v_cvt_f32_ubyte3_e32 v15, v12
	v_cvt_f32_ubyte2_e32 v14, v12
	v_cvt_f32_ubyte1_e32 v11, v12
	v_cvt_f32_ubyte0_e32 v10, v12
	v_cvt_f32_ubyte3_e32 v17, v13
	v_cvt_f32_ubyte2_e32 v16, v13
	v_pk_mul_f32 v[12:13], v[20:21], s[72:73] op_sel_hi:[1,0]
	global_load_dwordx4 v[20:23], v[18:19], off offset:256
	v_pk_mul_f32 v[10:11], v[10:11], s[72:73] op_sel_hi:[1,0]
	v_pk_mul_f32 v[14:15], v[14:15], s[72:73] op_sel_hi:[1,0]
	v_pk_mul_f32 v[16:17], v[16:17], s[72:73] op_sel_hi:[1,0]
	s_waitcnt vmcnt(0)
	v_lshlrev_b32_e32 v24, 16, v20
	v_and_b32_e32 v25, 0xffff0000, v20
	v_lshlrev_b32_e32 v20, 16, v21
	v_and_b32_e32 v21, 0xffff0000, v21
	v_pk_fma_f32 v[8:9], v[8:9], v[14:15], v[20:21]
	v_pk_fma_f32 v[6:7], v[6:7], v[10:11], v[24:25]
	v_lshlrev_b32_e32 v10, 16, v22
	v_and_b32_e32 v11, 0xffff0000, v22
	v_lshlrev_b32_e32 v14, 16, v23
	v_and_b32_e32 v15, 0xffff0000, v23
	v_pk_fma_f32 v[14:15], v[4:5], v[16:17], v[14:15]
	v_pk_fma_f32 v[4:5], v[2:3], v[12:13], v[10:11]
	v_cvt_pk_bf16_f32 v2, v6, v7
	v_cvt_pk_bf16_f32 v3, v8, v9
	v_cvt_pk_bf16_f32 v4, v4, v5
	v_cvt_pk_bf16_f32 v5, v14, v15
	global_store_dwordx4 v[18:19], v[2:5], off offset:256
	s_cmp_lg_u32 s48, 2
	s_cbranch_scc1 .Lmg_wskip1
	s_load_dwordx2 s[30:31], s[68:69], 0xc0
	v_readlane_b32 s32, v255, 2
	s_waitcnt vmcnt(0)
	buffer_wbl2 sc1
	v_mov_b32_e32 v2, s34
	v_mul_u32_u24_e32 v2, 0xaaab, v2
	v_lshrrev_b32_e32 v2, 17, v2
	s_lshl_b32 s32, s32, 4
	v_add_u32_e32 v2, s32, v2
	v_add_u32_e32 v2, 8, v2
	v_lshlrev_b32_e32 v2, 4, v2
	v_add_u32_e32 v2, 0x7600, v2
	v_mov_b32_e32 v3, 1
	s_waitcnt vmcnt(0) lgkmcnt(0)
	global_atomic_add v2, v3, s[30:31]
.Lmg_wskip1:
	s_cbranch_vccnz .LBB0_523
	s_andn2_b64 vcc, exec, s[2:3]
	s_cbranch_vccnz .LBB0_522
	s_barrier
	s_branch .LBB0_522

;     __host__ __device__ bool next(int i, Unit& u) const {
;         const long L = (long)i * G + c; if (L >= nwg) return false;
;         int wgid = (int)L; { const int q = nwg / NXCD, r = nwg % NXCD, xcd = wgid % NXCD, off = wgid / NXCD; wgid = (xcd < r ? xcd * (q + 1) : r * (q + 1) + (xcd - r) * q) + off; }
;         const int nig = WGM * nN, gid = wgid / nig, fm = gid * WGM, gsz = (nM - fm) < WGM ? (nM - fm) : WGM;
;         u.pm = fm + ((wgid % nig) % gsz); u.pn = (wgid % nig) / gsz; u.koff = 0; u.nt = 0; return true;
.LBB0_540:
	s_add_i32 s47, s47, 1
	s_mul_i32 s4, s34, 0xaaab
	s_lshr_b32 s4, s4, 17
	s_mul_i32 s5, s4, 3
	s_sub_i32 s5, s34, s5
	s_cmp_eq_u32 s5, 2
	s_cselect_b32 s5, 0, 0x10000000
	s_cmp_lt_u32 s34, 24
	s_cselect_b32 s5, s5, 0x10000000
	s_lshl_b32 s18, s47, 8
	s_add_i32 s18, s18, s4
	s_add_i32 s18, s18, s5
	s_mov_b32 s19, 0
	s_cmp_lg_u32 s47, 2
	s_cbranch_scc1 .Lmg_rskip2
	s_load_dwordx2 s[30:31], s[68:69], 0xc0
	v_readlane_b32 s5, v255, 2
	s_lshl_b32 s5, s5, 4
	s_add_i32 s5, s5, s4
	s_add_i32 s5, s5, 8
	s_lshl_b32 s5, s5, 4
	s_addk_i32 s5, 0x7600
	v_mov_b32_e32 v2, s5
	s_mov_b32 s4, 0
	s_waitcnt lgkmcnt(0)
.Lmg_spin2:
	global_load_dword v3, v2, s[30:31] sc1
	s_waitcnt vmcnt(0)
	v_readfirstlane_b32 s5, v3
	s_cmp_ge_u32 s5, 0x200
	s_cbranch_scc1 .Lmg_done2
	s_sleep 1
	s_add_i32 s4, s4, 1
	s_cmp_lt_u32 s4, 0x4000
	s_cbranch_scc1 .Lmg_spin2

;     __host__ __device__ bool next(int i, Unit& u) const {
;         const long L = (long)i * G + c; if (L >= nwg) return false;
;         int wgid = (int)L; { const int q = nwg / NXCD, r = nwg % NXCD, xcd = wgid % NXCD, off = wgid / NXCD; wgid = (xcd < r ? xcd * (q + 1) : r * (q + 1) + (xcd - r) * q) + off; }
;         const int nig = WGM * nN, gid = wgid / nig, fm = gid * WGM, gsz = (nM - fm) < WGM ? (nM - fm) : WGM;
;         u.pm = fm + ((wgid % nig) % gsz); u.pn = (wgid % nig) / gsz; u.koff = 0; u.nt = 0; return true;
.Lmg_rskip2:
	v_mov_b64_e32 v[2:3], s[94:95]
	v_cmp_ge_i64_e32 vcc, s[18:19], v[2:3]
	v_cmp_lt_i64_e64 s[4:5], s[18:19], v[2:3]
	s_cbranch_vccnz .LBB0_542
	s_ashr_i32 s14, s18, 31
	s_lshr_b32 s14, s14, 29
	s_add_i32 s14, s18, s14
	s_ashr_i32 s15, s14, 3
	s_and_b32 s14, s14, -8
	s_sub_i32 s14, s18, s14
	s_cmp_lt_i32 s14, 0
	s_cselect_b32 s16, s41, s39
	s_mul_i32 s14, s16, s14
	s_add_i32 s14, s14, s15
	s_ashr_i32 s15, s14, 31
	s_lshr_b32 s15, s15, 27
	s_add_i32 s15, s14, s15
	s_ashr_i32 s16, s15, 5
	s_lshl_b32 s16, s16, 3
	s_sub_i32 s17, s50, s16
	s_min_i32 s17, s17, 8
	s_abs_i32 s18, s17
	v_cvt_f32_u32_e32 v2, s18
	s_sub_i32 s20, 0, s18
	s_andn2_b32 s15, s15, 31
	s_sub_i32 s15, s14, s15
	v_rcp_iflag_f32_e32 v2, v2
	s_abs_i32 s14, s15
	s_xor_b32 s19, s15, s17
	s_ashr_i32 s19, s19, 31
	v_mul_f32_e32 v2, 0x4f7ffffe, v2
	v_cvt_u32_f32_e32 v2, v2
	s_nop 0
	v_readfirstlane_b32 s21, v2
	s_mul_i32 s20, s20, s21
	s_mul_hi_u32 s20, s21, s20
	s_add_i32 s21, s21, s20
	s_mul_hi_u32 s20, s14, s21
	s_mul_i32 s21, s20, s18
	s_sub_i32 s14, s14, s21
	s_add_i32 s23, s20, 1
	s_sub_i32 s21, s14, s18
	s_cmp_ge_u32 s14, s18
	s_cselect_b32 s20, s23, s20
	s_cselect_b32 s14, s21, s14
	s_add_i32 s21, s20, 1
	s_cmp_ge_u32 s14, s18
	s_cselect_b32 s14, s21, s20
	s_xor_b32 s14, s14, s19
	s_sub_i32 s14, s14, s19
	s_mul_i32 s17, s14, s17
	s_sub_i32 s15, s15, s17
	s_add_i32 s16, s15, s16
